# adds: LRU heavy pass gate-weight LDS fragments read 8 ahead of their MFMAs (both channel halves)
# speedup vs baseline: 1.0018x; 1.0018x over previous
.LBB0_473:
	v_lshl_add_u32 v68, v68, 2, 0
	ds_read_b128 v[70:73], v68 offset:47104
	ds_read_b128 v[74:77], v68 offset:47120
	ds_read_b128 v[78:81], v68 offset:46080
	ds_read_b128 v[82:85], v68 offset:46096
	s_waitcnt vmcnt(19)
	v_lshlrev_b32_e32 v86, 16, v62
	v_and_b32_e32 v87, 0xffff0000, v62
	v_lshlrev_b32_e32 v62, 16, v63
	v_and_b32_e32 v63, 0xffff0000, v63
	s_waitcnt lgkmcnt(1)
	v_pk_fma_f32 v[80:81], v[80:81], v[62:63], v[72:73]
	v_lshlrev_b32_e32 v62, 16, v64
	v_and_b32_e32 v63, 0xffff0000, v64
	s_waitcnt lgkmcnt(0)
	v_pk_fma_f32 v[74:75], v[82:83], v[62:63], v[74:75]
	v_lshlrev_b32_e32 v62, 16, v65
	v_and_b32_e32 v63, 0xffff0000, v65
	v_pk_fma_f32 v[78:79], v[78:79], v[86:87], v[70:71]
	v_pk_fma_f32 v[76:77], v[84:85], v[62:63], v[76:77]
	ds_read_b128 v[62:65], v68 offset:46336
	ds_read_b128 v[70:73], v68 offset:46352
	s_waitcnt vmcnt(15)
	v_lshlrev_b32_e32 v82, 16, v58
	v_and_b32_e32 v83, 0xffff0000, v58
	v_lshlrev_b32_e32 v58, 16, v59
	v_and_b32_e32 v59, 0xffff0000, v59
	s_waitcnt lgkmcnt(1)
	v_pk_fma_f32 v[80:81], v[64:65], v[58:59], v[80:81]
	v_lshlrev_b32_e32 v58, 16, v60
	v_and_b32_e32 v59, 0xffff0000, v60
	s_waitcnt lgkmcnt(0)
	v_pk_fma_f32 v[70:71], v[70:71], v[58:59], v[74:75]
	v_lshlrev_b32_e32 v58, 16, v61
	v_and_b32_e32 v59, 0xffff0000, v61
	v_pk_fma_f32 v[78:79], v[62:63], v[82:83], v[78:79]
	v_pk_fma_f32 v[72:73], v[72:73], v[58:59], v[76:77]
	ds_read_b128 v[58:61], v68 offset:46592
	ds_read_b128 v[62:65], v68 offset:46608
	s_waitcnt vmcnt(11)
	v_lshlrev_b32_e32 v74, 16, v54
	v_and_b32_e32 v75, 0xffff0000, v54
	v_lshlrev_b32_e32 v54, 16, v55
	v_and_b32_e32 v55, 0xffff0000, v55
	s_waitcnt lgkmcnt(1)
	v_pk_fma_f32 v[76:77], v[60:61], v[54:55], v[80:81]
	v_lshlrev_b32_e32 v54, 16, v56
	v_and_b32_e32 v55, 0xffff0000, v56
	s_waitcnt lgkmcnt(0)
	v_pk_fma_f32 v[62:63], v[62:63], v[54:55], v[70:71]
	v_lshlrev_b32_e32 v54, 16, v57
	v_and_b32_e32 v55, 0xffff0000, v57
	v_pk_fma_f32 v[74:75], v[58:59], v[74:75], v[78:79]
	v_pk_fma_f32 v[64:65], v[64:65], v[54:55], v[72:73]
	ds_read_b128 v[54:57], v68 offset:46848
	ds_read_b128 v[58:61], v68 offset:46864
	s_waitcnt vmcnt(7)
	v_lshlrev_b32_e32 v70, 16, v50
	v_and_b32_e32 v71, 0xffff0000, v50
	v_lshlrev_b32_e32 v50, 16, v51
	v_and_b32_e32 v51, 0xffff0000, v51
	s_waitcnt lgkmcnt(1)
	v_pk_fma_f32 v[50:51], v[56:57], v[50:51], v[76:77]
	v_lshlrev_b32_e32 v56, 16, v52
	v_and_b32_e32 v57, 0xffff0000, v52
	v_lshlrev_b32_e32 v52, 16, v53
	v_and_b32_e32 v53, 0xffff0000, v53
	v_pk_fma_f32 v[54:55], v[54:55], v[70:71], v[74:75]
	s_waitcnt lgkmcnt(0)
	v_pk_fma_f32 v[56:57], v[58:59], v[56:57], v[62:63]
	v_pk_fma_f32 v[52:53], v[60:61], v[52:53], v[64:65]
	v_cvt_pk_bf16_f32 v122, v54, v55
	v_cvt_pk_bf16_f32 v123, v50, v51
	v_cvt_pk_bf16_f32 v124, v56, v57
	v_cvt_pk_bf16_f32 v125, v52, v53
	ds_read_b128 v[50:53], v68 offset:47168
	ds_read_b128 v[54:57], v68 offset:47184
	ds_read_b128 v[58:61], v68 offset:46144
	ds_read_b128 v[62:65], v68 offset:46160
	v_lshlrev_b32_e32 v70, 16, v46
	v_and_b32_e32 v71, 0xffff0000, v46
	v_lshlrev_b32_e32 v46, 16, v47
	v_and_b32_e32 v47, 0xffff0000, v47
	s_waitcnt lgkmcnt(1)
	v_pk_fma_f32 v[60:61], v[60:61], v[46:47], v[52:53]
	v_lshlrev_b32_e32 v46, 16, v48
	v_and_b32_e32 v47, 0xffff0000, v48
	s_waitcnt lgkmcnt(0)
	v_pk_fma_f32 v[54:55], v[62:63], v[46:47], v[54:55]
	v_lshlrev_b32_e32 v46, 16, v49
	v_and_b32_e32 v47, 0xffff0000, v49
	v_pk_fma_f32 v[58:59], v[58:59], v[70:71], v[50:51]
	v_pk_fma_f32 v[56:57], v[64:65], v[46:47], v[56:57]
	ds_read_b128 v[46:49], v68 offset:46400
	ds_read_b128 v[50:53], v68 offset:46416
	v_lshlrev_b32_e32 v62, 16, v42
	v_and_b32_e32 v63, 0xffff0000, v42
	v_lshlrev_b32_e32 v42, 16, v43
	v_and_b32_e32 v43, 0xffff0000, v43
	s_waitcnt lgkmcnt(1)
	v_pk_fma_f32 v[60:61], v[48:49], v[42:43], v[60:61]
	v_lshlrev_b32_e32 v42, 16, v44
	v_and_b32_e32 v43, 0xffff0000, v44
	s_waitcnt lgkmcnt(0)
	v_pk_fma_f32 v[50:51], v[50:51], v[42:43], v[54:55]
	v_lshlrev_b32_e32 v42, 16, v45
	v_and_b32_e32 v43, 0xffff0000, v45
	v_pk_fma_f32 v[58:59], v[46:47], v[62:63], v[58:59]
	v_pk_fma_f32 v[52:53], v[52:53], v[42:43], v[56:57]
	ds_read_b128 v[42:45], v68 offset:46656
	ds_read_b128 v[46:49], v68 offset:46672
	v_lshlrev_b32_e32 v54, 16, v38
	v_and_b32_e32 v55, 0xffff0000, v38
	v_lshlrev_b32_e32 v38, 16, v39
	v_and_b32_e32 v39, 0xffff0000, v39
	s_waitcnt lgkmcnt(1)
	v_pk_fma_f32 v[56:57], v[44:45], v[38:39], v[60:61]
	v_lshlrev_b32_e32 v38, 16, v40
	v_and_b32_e32 v39, 0xffff0000, v40
	s_waitcnt lgkmcnt(0)
	v_pk_fma_f32 v[46:47], v[46:47], v[38:39], v[50:51]
	v_lshlrev_b32_e32 v38, 16, v41
	v_and_b32_e32 v39, 0xffff0000, v41
	v_pk_fma_f32 v[54:55], v[42:43], v[54:55], v[58:59]
	v_pk_fma_f32 v[48:49], v[48:49], v[38:39], v[52:53]
	ds_read_b128 v[38:41], v68 offset:46912
	ds_read_b128 v[42:45], v68 offset:46928
	s_waitcnt vmcnt(6)
	v_lshlrev_b32_e32 v50, 16, v34
	v_and_b32_e32 v51, 0xffff0000, v34
	v_lshlrev_b32_e32 v34, 16, v35
	v_and_b32_e32 v35, 0xffff0000, v35
	s_waitcnt lgkmcnt(1)
	v_pk_fma_f32 v[34:35], v[40:41], v[34:35], v[56:57]
	v_lshlrev_b32_e32 v40, 16, v36
	v_and_b32_e32 v41, 0xffff0000, v36
	v_lshlrev_b32_e32 v36, 16, v37
	v_and_b32_e32 v37, 0xffff0000, v37
	v_pk_fma_f32 v[38:39], v[38:39], v[50:51], v[54:55]
	s_waitcnt lgkmcnt(0)
	v_pk_fma_f32 v[40:41], v[42:43], v[40:41], v[46:47]
	v_pk_fma_f32 v[36:37], v[44:45], v[36:37], v[48:49]
	v_cvt_pk_bf16_f32 v126, v38, v39
	v_cvt_pk_bf16_f32 v127, v34, v35
	v_cvt_pk_bf16_f32 v128, v40, v41
	v_cvt_pk_bf16_f32 v129, v36, v37
	ds_read_b128 v[34:37], v68 offset:47232
	ds_read_b128 v[38:41], v68 offset:47248
	ds_read_b128 v[42:45], v68 offset:46208
	ds_read_b128 v[46:49], v68 offset:46224
	v_lshlrev_b32_e32 v50, 16, v30
	v_and_b32_e32 v51, 0xffff0000, v30
	v_lshlrev_b32_e32 v30, 16, v31
	v_and_b32_e32 v31, 0xffff0000, v31
	s_waitcnt lgkmcnt(1)
	v_pk_fma_f32 v[44:45], v[44:45], v[30:31], v[36:37]
	v_lshlrev_b32_e32 v30, 16, v32
	v_and_b32_e32 v31, 0xffff0000, v32
	s_waitcnt lgkmcnt(0)
	v_pk_fma_f32 v[38:39], v[46:47], v[30:31], v[38:39]
	v_lshlrev_b32_e32 v30, 16, v33
	v_and_b32_e32 v31, 0xffff0000, v33
	v_pk_fma_f32 v[42:43], v[42:43], v[50:51], v[34:35]
	v_pk_fma_f32 v[40:41], v[48:49], v[30:31], v[40:41]
	ds_read_b128 v[30:33], v68 offset:46464
	ds_read_b128 v[34:37], v68 offset:46480
	v_lshlrev_b32_e32 v46, 16, v26
	v_and_b32_e32 v47, 0xffff0000, v26
	v_lshlrev_b32_e32 v26, 16, v27
	v_and_b32_e32 v27, 0xffff0000, v27
	s_waitcnt lgkmcnt(1)
	v_pk_fma_f32 v[44:45], v[32:33], v[26:27], v[44:45]
	v_lshlrev_b32_e32 v26, 16, v28
	v_and_b32_e32 v27, 0xffff0000, v28
	s_waitcnt lgkmcnt(0)
	v_pk_fma_f32 v[34:35], v[34:35], v[26:27], v[38:39]
	v_lshlrev_b32_e32 v26, 16, v29
	v_and_b32_e32 v27, 0xffff0000, v29
	v_pk_fma_f32 v[42:43], v[30:31], v[46:47], v[42:43]
	v_pk_fma_f32 v[36:37], v[36:37], v[26:27], v[40:41]
	ds_read_b128 v[26:29], v68 offset:46720
	ds_read_b128 v[30:33], v68 offset:46736
	v_lshlrev_b32_e32 v38, 16, v18
	v_and_b32_e32 v39, 0xffff0000, v18
	v_lshlrev_b32_e32 v18, 16, v19
	v_and_b32_e32 v19, 0xffff0000, v19
	s_waitcnt lgkmcnt(1)
	v_pk_fma_f32 v[40:41], v[28:29], v[18:19], v[44:45]
	v_lshlrev_b32_e32 v18, 16, v20
	v_and_b32_e32 v19, 0xffff0000, v20
	s_waitcnt lgkmcnt(0)
	v_pk_fma_f32 v[30:31], v[30:31], v[18:19], v[34:35]
	v_lshlrev_b32_e32 v18, 16, v21
	v_and_b32_e32 v19, 0xffff0000, v21
	v_pk_fma_f32 v[38:39], v[26:27], v[38:39], v[42:43]
	v_pk_fma_f32 v[32:33], v[32:33], v[18:19], v[36:37]
	ds_read_b128 v[18:21], v68 offset:46976
	ds_read_b128 v[26:29], v68 offset:46992
	s_waitcnt vmcnt(5)
	v_lshlrev_b32_e32 v34, 16, v22
	v_and_b32_e32 v35, 0xffff0000, v22
	v_lshlrev_b32_e32 v22, 16, v23
	v_and_b32_e32 v23, 0xffff0000, v23
	s_waitcnt lgkmcnt(1)
	v_pk_fma_f32 v[20:21], v[20:21], v[22:23], v[40:41]
	v_lshlrev_b32_e32 v22, 16, v24
	v_and_b32_e32 v23, 0xffff0000, v24
	v_lshlrev_b32_e32 v24, 16, v25
	v_and_b32_e32 v25, 0xffff0000, v25
	v_pk_fma_f32 v[18:19], v[18:19], v[34:35], v[38:39]
	s_waitcnt lgkmcnt(0)
	v_pk_fma_f32 v[22:23], v[26:27], v[22:23], v[30:31]
	v_pk_fma_f32 v[24:25], v[28:29], v[24:25], v[32:33]
	v_cvt_pk_bf16_f32 v130, v18, v19
	v_cvt_pk_bf16_f32 v131, v20, v21
	v_cvt_pk_bf16_f32 v132, v22, v23
	v_cvt_pk_bf16_f32 v133, v24, v25
	ds_read_b128 v[18:21], v68 offset:47296
	ds_read_b128 v[22:25], v68 offset:47312
	ds_read_b128 v[26:29], v68 offset:46272
	ds_read_b128 v[30:33], v68 offset:46288
	v_lshlrev_b32_e32 v34, 16, v14
	v_and_b32_e32 v35, 0xffff0000, v14
	v_lshlrev_b32_e32 v14, 16, v15
	v_and_b32_e32 v15, 0xffff0000, v15
	s_waitcnt lgkmcnt(1)
	v_pk_fma_f32 v[28:29], v[28:29], v[14:15], v[20:21]
	v_lshlrev_b32_e32 v14, 16, v16
	v_and_b32_e32 v15, 0xffff0000, v16
	s_waitcnt lgkmcnt(0)
	v_pk_fma_f32 v[22:23], v[30:31], v[14:15], v[22:23]
	v_lshlrev_b32_e32 v14, 16, v17
	v_and_b32_e32 v15, 0xffff0000, v17
	v_pk_fma_f32 v[26:27], v[26:27], v[34:35], v[18:19]
	v_pk_fma_f32 v[24:25], v[32:33], v[14:15], v[24:25]
	ds_read_b128 v[14:17], v68 offset:46528
	ds_read_b128 v[18:21], v68 offset:46544
	v_lshlrev_b32_e32 v30, 16, v6
	v_and_b32_e32 v31, 0xffff0000, v6
	v_lshlrev_b32_e32 v6, 16, v7
	v_and_b32_e32 v7, 0xffff0000, v7
	s_waitcnt lgkmcnt(1)
	v_pk_fma_f32 v[28:29], v[16:17], v[6:7], v[28:29]
	v_lshlrev_b32_e32 v6, 16, v8
	v_and_b32_e32 v7, 0xffff0000, v8
	s_waitcnt lgkmcnt(0)
	v_pk_fma_f32 v[18:19], v[18:19], v[6:7], v[22:23]
	v_lshlrev_b32_e32 v6, 16, v9
	v_and_b32_e32 v7, 0xffff0000, v9
	v_pk_fma_f32 v[26:27], v[14:15], v[30:31], v[26:27]
	v_pk_fma_f32 v[20:21], v[20:21], v[6:7], v[24:25]
	ds_read_b128 v[6:9], v68 offset:46784
	ds_read_b128 v[14:17], v68 offset:46800
	v_lshlrev_b32_e32 v22, 16, v2
	v_and_b32_e32 v23, 0xffff0000, v2
	v_lshlrev_b32_e32 v2, 16, v3
	v_and_b32_e32 v3, 0xffff0000, v3
	s_waitcnt lgkmcnt(1)
	v_pk_fma_f32 v[24:25], v[8:9], v[2:3], v[28:29]
	v_lshlrev_b32_e32 v2, 16, v4
	v_and_b32_e32 v3, 0xffff0000, v4
	s_waitcnt lgkmcnt(0)
	v_pk_fma_f32 v[14:15], v[14:15], v[2:3], v[18:19]
	v_lshlrev_b32_e32 v2, 16, v5
	v_and_b32_e32 v3, 0xffff0000, v5
	v_pk_fma_f32 v[22:23], v[6:7], v[22:23], v[26:27]
	v_pk_fma_f32 v[16:17], v[16:17], v[2:3], v[20:21]
	ds_read_b128 v[2:5], v68 offset:47040
	ds_read_b128 v[6:9], v68 offset:47056
	s_waitcnt vmcnt(4)
	v_lshlrev_b32_e32 v18, 16, v10
	v_and_b32_e32 v19, 0xffff0000, v10
	v_lshlrev_b32_e32 v10, 16, v11
	v_and_b32_e32 v11, 0xffff0000, v11
	s_waitcnt lgkmcnt(1)
	v_pk_fma_f32 v[4:5], v[4:5], v[10:11], v[24:25]
	v_pk_fma_f32 v[2:3], v[2:3], v[18:19], v[22:23]
	v_cvt_pk_bf16_f32 v119, v4, v5
	v_and_b32_e32 v4, 64, v229
	v_cvt_pk_bf16_f32 v118, v2, v3
	v_xor_b32_e32 v3, 32, v229
	v_add_u32_e32 v4, 64, v4
	v_lshlrev_b32_e32 v10, 16, v12
	v_and_b32_e32 v11, 0xffff0000, v12
	v_cmp_lt_i32_e32 vcc, v3, v4
	s_waitcnt lgkmcnt(0)
	v_pk_fma_f32 v[6:7], v[6:7], v[10:11], v[14:15]
	v_lshlrev_b32_e32 v2, 4, v177
	v_cndmask_b32_e32 v3, v229, v3, vcc
	v_cvt_pk_bf16_f32 v120, v6, v7
	v_sub_u32_e32 v6, v68, v2
	v_lshlrev_b32_e32 v176, 2, v3
	v_ashrrev_i32_e32 v3, 31, v2
	v_lshlrev_b64 v[4:5], 9, v[66:67]
	v_lshl_add_u64 v[2:3], v[2:3], 0, s[56:57]
	v_mad_u32_u24 v179, v170, s50, v6
	v_lshl_add_u64 v[148:149], v[2:3], 0, v[4:5]
	ds_read_b128 v[202:205], v179
	ds_read_b128 v[206:209], v179 offset:32
	ds_read_b128 v[210:213], v179 offset:9216
	ds_read_b128 v[214:217], v179 offset:9248
	ds_read_b128 v[218:221], v179 offset:18432
	ds_read_b128 v[222:225], v179 offset:18464
	ds_read_b128 v[238:241], v179 offset:27648
	ds_read_b128 v[242:245], v179 offset:27680
	ds_read_b128 v[150:153], v179 offset:36864
	s_nop 0
	s_waitcnt lgkmcnt(8)
	v_mfma_f32_32x32x16_bf16 v[82:97], v[122:125], v[202:205], 0
	ds_read_b128 v[202:205], v179 offset:36896
	v_lshlrev_b32_e32 v10, 16, v13
	v_and_b32_e32 v11, 0xffff0000, v13
	v_fma_f32 v8, v8, v10, v16
	v_fma_f32 v9, v9, v11, v17
	v_lshl_add_u32 v178, v170, 2, 0
	v_cvt_pk_bf16_f32 v121, v8, v9
	v_cmp_gt_u32_e64 s[40:41], 32, v175
	s_waitcnt lgkmcnt(8)
	v_mfma_f32_32x32x16_bf16 v[82:97], v[126:129], v[206:209], v[82:97]
	ds_read_b128 v[206:209], v179 offset:64
	s_movk_i32 s0, 0x140
	v_mul_u32_u24_e32 v181, 0x50, v170
	v_and_b32_e32 v182, 0xffffffe0, v175
	s_waitcnt lgkmcnt(8)
	v_mfma_f32_32x32x16_bf16 v[66:81], v[122:125], v[210:213], 0
	ds_read_b128 v[210:213], v179 offset:9280
	s_waitcnt lgkmcnt(8)
	v_mfma_f32_32x32x16_bf16 v[66:81], v[126:129], v[214:217], v[66:81]
	ds_read_b128 v[214:217], v179 offset:18496
	s_waitcnt lgkmcnt(8)
	v_mfma_f32_32x32x16_bf16 v[50:65], v[122:125], v[218:221], 0
	ds_read_b128 v[218:221], v179 offset:27712
	s_waitcnt lgkmcnt(8)
	v_mfma_f32_32x32x16_bf16 v[50:65], v[126:129], v[222:225], v[50:65]
	ds_read_b128 v[222:225], v179 offset:36928
	s_waitcnt lgkmcnt(8)
	v_mfma_f32_32x32x16_bf16 v[34:49], v[122:125], v[238:241], 0
	ds_read_b128 v[238:241], v179 offset:96
	s_waitcnt lgkmcnt(8)
	v_mfma_f32_32x32x16_bf16 v[34:49], v[126:129], v[242:245], v[34:49]
	ds_read_b128 v[242:245], v179 offset:9312
	s_waitcnt lgkmcnt(8)
	v_mfma_f32_32x32x16_bf16 v[18:33], v[122:125], v[150:153], 0
	s_waitcnt vmcnt(3)
	v_mfma_f32_32x32x16_bf16 v[2:17], v[114:117], v[150:153], 0
	ds_read_b128 v[150:153], v179 offset:18528
	s_waitcnt lgkmcnt(8)
	v_mfma_f32_32x32x16_bf16 v[18:33], v[126:129], v[202:205], v[18:33]
	s_waitcnt vmcnt(2)
	v_mfma_f32_32x32x16_bf16 v[2:17], v[110:113], v[202:205], v[2:17]
	ds_read_b128 v[202:205], v179 offset:27744
	s_waitcnt lgkmcnt(8)
	v_mfma_f32_32x32x16_bf16 v[82:97], v[130:133], v[206:209], v[82:97]
	ds_read_b128 v[206:209], v179 offset:36960
	s_waitcnt lgkmcnt(8)
	v_mfma_f32_32x32x16_bf16 v[66:81], v[130:133], v[210:213], v[66:81]
	s_nop 0
	s_waitcnt lgkmcnt(7)
	v_mfma_f32_32x32x16_bf16 v[50:65], v[130:133], v[214:217], v[50:65]
	s_nop 0
	s_waitcnt lgkmcnt(6)
	v_mfma_f32_32x32x16_bf16 v[34:49], v[130:133], v[218:221], v[34:49]
	s_nop 0
	s_waitcnt lgkmcnt(5)
	v_mfma_f32_32x32x16_bf16 v[18:33], v[130:133], v[222:225], v[18:33]
	s_waitcnt vmcnt(1)
	v_mfma_f32_32x32x16_bf16 v[2:17], v[106:109], v[222:225], v[2:17]
	s_nop 0
	s_waitcnt lgkmcnt(4)
	v_mfma_f32_32x32x16_bf16 v[82:97], v[118:121], v[238:241], v[82:97]
	s_nop 0
	s_waitcnt lgkmcnt(3)
	v_mfma_f32_32x32x16_bf16 v[66:81], v[118:121], v[242:245], v[66:81]
	s_nop 0
	s_waitcnt lgkmcnt(2)
	v_mfma_f32_32x32x16_bf16 v[50:65], v[118:121], v[150:153], v[50:65]
	s_nop 0
	s_waitcnt lgkmcnt(1)
	v_mfma_f32_32x32x16_bf16 v[34:49], v[118:121], v[202:205], v[34:49]
	s_nop 0
	ds_read2st64_b32 v[160:161], v178 offset0:185 offset1:186
	ds_read2st64_b32 v[154:155], v178 offset0:187 offset1:188
	ds_read2st64_b32 v[156:157], v178 offset0:189 offset1:190
	s_waitcnt lgkmcnt(2)
	v_mov_b32_e32 v158, v161
	s_waitcnt lgkmcnt(1)
	v_mov_b32_e32 v100, v155
	v_pk_add_f32 v[66:67], v[66:67], v[158:159] op_sel_hi:[1,0]
	s_nop 2
	v_pk_add_f32 v[34:35], v[34:35], v[100:101] op_sel_hi:[1,0]
	v_exp_f32_e32 v66, v66
	v_exp_f32_e32 v67, v67
	v_exp_f32_e32 v34, v34
	v_exp_f32_e32 v35, v35
	v_mfma_f32_32x32x16_bf16 v[18:33], v[118:121], v[206:209], v[18:33]
	v_add_f32_e64 v66, v66, 1.0
	v_add_f32_e64 v67, v67, 1.0
	v_add_f32_e64 v82, v82, v160
	v_add_f32_e64 v83, v83, v160
	v_add_f32_e64 v34, v34, 1.0
	v_add_f32_e64 v35, v35, 1.0
	v_rcp_f32_e32 v146, v66
	v_rcp_f32_e32 v147, v67
	v_rcp_f32_e32 v34, v34
	v_rcp_f32_e32 v35, v35
	s_waitcnt vmcnt(0)
	v_mfma_f32_32x32x16_bf16 v[2:17], v[102:105], v[206:209], v[2:17]
	v_mul_f32_e64 v146, v18, v146
	v_mul_f32_e64 v147, v19, v147
	v_exp_f32_e32 v82, v82
	v_pk_mul_f32 v[152:153], v[18:19], v[34:35]
	v_pk_add_f32 v[18:19], v[84:85], v[160:161] op_sel_hi:[1,0]
	v_exp_f32_e32 v83, v83
	v_exp_f32_e32 v18, v18
	v_exp_f32_e32 v19, v19
	v_pk_add_f32 v[50:51], v[50:51], v[154:155] op_sel_hi:[1,0]
	v_pk_add_f32 v[82:83], v[82:83], 1.0 op_sel_hi:[1,0]
	v_pk_add_f32 v[34:35], v[68:69], v[158:159] op_sel_hi:[1,0]
	v_pk_add_f32 v[18:19], v[18:19], 1.0 op_sel_hi:[1,0]
	v_rcp_f32_e32 v82, v82
	v_rcp_f32_e32 v83, v83
	v_rcp_f32_e32 v18, v18
	v_rcp_f32_e32 v19, v19
	v_exp_f32_e32 v50, v50
	s_waitcnt lgkmcnt(0)
	v_pk_mul_f32 v[66:67], v[156:157], v[82:83] op_sel_hi:[0,1]
	v_exp_f32_e32 v51, v51
	v_exp_f32_e32 v34, v34
	v_exp_f32_e32 v35, v35
	v_pk_mul_f32 v[18:19], v[156:157], v[18:19] op_sel_hi:[0,1]
	v_exp_f32_e32 v66, v66
	v_exp_f32_e32 v67, v67
	v_exp_f32_e32 v84, v18
	v_exp_f32_e32 v85, v19
	v_pk_add_f32 v[50:51], v[50:51], 1.0 op_sel_hi:[1,0]
	v_pk_add_f32 v[34:35], v[34:35], 1.0 op_sel_hi:[1,0]
	v_pk_fma_f32 v[82:83], v[66:67], v[66:67], 1.0 op_sel_hi:[1,1,0] neg_lo:[1,0,0] neg_hi:[1,0,0]
	v_rcp_f32_e32 v50, v50
	v_rcp_f32_e32 v51, v51
	v_rcp_f32_e32 v34, v34
	v_rcp_f32_e32 v35, v35
	v_pk_fma_f32 v[18:19], v[84:85], v[84:85], 1.0 op_sel_hi:[1,1,0] neg_lo:[1,0,0] neg_hi:[1,0,0]
	v_sqrt_f32_e32 v82, v82
	v_sqrt_f32_e32 v83, v83
	v_sqrt_f32_e32 v18, v18
	v_sqrt_f32_e32 v19, v19
	v_mov_b32_e32 v98, v157
	v_pk_mul_f32 v[50:51], v[98:99], v[50:51] op_sel_hi:[0,1]
	v_pk_mul_f32 v[34:35], v[20:21], v[34:35]
	v_pk_mul_f32 v[82:83], v[146:147], v[82:83]
	v_exp_f32_e32 v147, v50
	v_exp_f32_e32 v150, v51
	v_pk_mul_f32 v[50:51], v[34:35], v[18:19]
	v_pk_add_f32 v[34:35], v[36:37], v[100:101] op_sel_hi:[1,0]
	v_pk_add_f32 v[38:39], v[38:39], v[100:101] op_sel_hi:[1,0]
	v_exp_f32_e32 v34, v34
	v_exp_f32_e32 v35, v35
	v_exp_f32_e32 v38, v38
	v_exp_f32_e32 v39, v39
	v_pk_add_f32 v[18:19], v[52:53], v[154:155] op_sel_hi:[1,0]
	v_pk_add_f32 v[34:35], v[34:35], 1.0 op_sel_hi:[1,0]
	v_exp_f32_e32 v18, v18
	v_rcp_f32_e32 v34, v34
	v_rcp_f32_e32 v35, v35
	v_pk_add_f32 v[38:39], v[38:39], 1.0 op_sel_hi:[1,0]
	v_exp_f32_e32 v19, v19
	v_fma_f32 v82, 0, v66, v82
	v_pk_mul_f32 v[68:69], v[20:21], v[34:35]
	v_pk_add_f32 v[20:21], v[86:87], v[160:161] op_sel_hi:[1,0]
	v_pk_add_f32 v[34:35], v[70:71], v[158:159] op_sel_hi:[1,0]
	v_exp_f32_e32 v20, v20
	v_exp_f32_e32 v21, v21
	v_exp_f32_e32 v34, v34
	v_exp_f32_e32 v35, v35
	v_pk_add_f32 v[18:19], v[18:19], 1.0 op_sel_hi:[1,0]
	v_pk_add_f32 v[20:21], v[20:21], 1.0 op_sel_hi:[1,0]
	v_rcp_f32_e32 v18, v18
	v_rcp_f32_e32 v20, v20
	v_rcp_f32_e32 v21, v21
	v_pk_add_f32 v[34:35], v[34:35], 1.0 op_sel_hi:[1,0]
	v_rcp_f32_e32 v19, v19
	v_rcp_f32_e32 v36, v34
	v_pk_mul_f32 v[20:21], v[156:157], v[20:21] op_sel_hi:[0,1]
	v_rcp_f32_e32 v37, v35
	v_exp_f32_e32 v34, v20
	v_exp_f32_e32 v35, v21
	v_pk_mul_f32 v[18:19], v[98:99], v[18:19] op_sel_hi:[0,1]
	v_pk_mul_f32 v[36:37], v[22:23], v[36:37]
	v_exp_f32_e32 v53, v18
	v_pk_fma_f32 v[20:21], v[34:35], v[34:35], 1.0 op_sel_hi:[1,1,0] neg_lo:[1,0,0] neg_hi:[1,0,0]
	v_fmac_f32_e32 v83, v67, v82
	v_sqrt_f32_e32 v20, v20
	v_sqrt_f32_e32 v21, v21
	v_fma_f32 v50, v84, v83, v50
	v_fmac_f32_e32 v51, v85, v50
	v_mul_f32_e32 v67, v66, v67
	v_pk_mul_f32 v[36:37], v[36:37], v[20:21]
	v_pk_add_f32 v[20:21], v[54:55], v[154:155] op_sel_hi:[1,0]
	v_rcp_f32_e32 v54, v38
	v_exp_f32_e32 v20, v20
	v_exp_f32_e32 v21, v21
	v_rcp_f32_e32 v55, v39
	v_fma_f32 v36, 0, v34, v36
	v_fmac_f32_e32 v37, v35, v36
	v_pk_add_f32 v[20:21], v[20:21], 1.0 op_sel_hi:[1,0]
	v_pk_mul_f32 v[54:55], v[22:23], v[54:55]
	v_rcp_f32_e32 v20, v20
	v_rcp_f32_e32 v21, v21
	v_pk_add_f32 v[22:23], v[72:73], v[158:159] op_sel_hi:[1,0]
	v_mov_b32_e32 v151, v147
	v_exp_f32_e32 v22, v22
	v_pk_mul_f32 v[20:21], v[98:99], v[20:21] op_sel_hi:[0,1]
	v_exp_f32_e32 v146, v20
	v_exp_f32_e32 v38, v21
	v_pk_add_f32 v[20:21], v[88:89], v[160:161] op_sel_hi:[1,0]
	v_exp_f32_e32 v23, v23
	v_exp_f32_e32 v20, v20
	v_exp_f32_e32 v21, v21
	v_exp_f32_e32 v19, v19
	v_pk_add_f32 v[22:23], v[22:23], 1.0 op_sel_hi:[1,0]
	v_pk_mul_f32 v[200:201], v[2:3], v[2:3]
	v_pk_add_f32 v[20:21], v[20:21], 1.0 op_sel_hi:[1,0]
	v_rcp_f32_e32 v22, v22
	v_rcp_f32_e32 v20, v20
	v_rcp_f32_e32 v21, v21
	v_rcp_f32_e32 v23, v23
	v_pk_mul_f32 v[200:201], v[2:3], v[200:201]
	v_pk_mul_f32 v[20:21], v[156:157], v[20:21] op_sel_hi:[0,1]
	v_exp_f32_e32 v101, v21
	v_pk_mul_f32 v[88:89], v[24:25], v[22:23]
	v_exp_f32_e32 v162, v20
	v_pk_add_f32 v[20:21], v[56:57], v[154:155] op_sel_hi:[1,0]
	v_pk_add_f32 v[22:23], v[40:41], v[100:101] op_sel_hi:[1,0]
	v_exp_f32_e32 v20, v20
	v_exp_f32_e32 v22, v22
	v_exp_f32_e32 v23, v23
	v_exp_f32_e32 v21, v21
	v_mul_f32_e32 v56, v34, v35
	v_pk_fma_f32 v[200:201], v[200:201], s[54:55], v[2:3] op_sel_hi:[1,0,1]
	v_pk_add_f32 v[22:23], v[22:23], 1.0 op_sel_hi:[1,0]
	v_pk_add_f32 v[20:21], v[20:21], 1.0 op_sel_hi:[1,0]
	v_rcp_f32_e32 v22, v22
	v_rcp_f32_e32 v23, v23
	v_rcp_f32_e32 v20, v20
	v_rcp_f32_e32 v21, v21
	v_pk_mul_f32 v[200:201], v[200:201], s[28:29] op_sel_hi:[1,0]
	v_pk_mul_f32 v[70:71], v[24:25], v[22:23]
	v_pk_add_f32 v[22:23], v[74:75], v[158:159] op_sel_hi:[1,0]
	v_pk_add_f32 v[24:25], v[42:43], v[100:101] op_sel_hi:[1,0]
	v_exp_f32_e32 v22, v22
	v_exp_f32_e32 v23, v23
	v_exp_f32_e32 v24, v24
	v_exp_f32_e32 v25, v25
	v_pk_mul_f32 v[20:21], v[98:99], v[20:21] op_sel_hi:[0,1]
	v_pk_add_f32 v[22:23], v[22:23], 1.0 op_sel_hi:[1,0]
	v_exp_f32_e32 v52, v20
	v_rcp_f32_e32 v22, v22
	v_rcp_f32_e32 v23, v23
	v_pk_add_f32 v[24:25], v[24:25], 1.0 op_sel_hi:[1,0]
	v_exp_f32_e32 v18, v21
	v_rcp_f32_e32 v24, v24
	v_pk_mul_f32 v[166:167], v[26:27], v[22:23]
	v_pk_add_f32 v[22:23], v[58:59], v[154:155] op_sel_hi:[1,0]
	v_rcp_f32_e32 v25, v25
	v_exp_f32_e32 v22, v22
	v_exp_f32_e32 v23, v23
	v_pk_add_f32 v[20:21], v[90:91], v[160:161] op_sel_hi:[1,0]
	v_pk_mul_f32 v[86:87], v[26:27], v[24:25]
	v_pk_add_f32 v[24:25], v[76:77], v[158:159] op_sel_hi:[1,0]
	v_pk_add_f32 v[22:23], v[22:23], 1.0 op_sel_hi:[1,0]
	v_exp_f32_e32 v24, v24
	v_rcp_f32_e32 v22, v22
	v_rcp_f32_e32 v23, v23
	v_exp_f32_e32 v25, v25
	v_exp_f32_e32 v20, v20
	v_exp_f32_e32 v21, v21
	v_pk_mul_f32 v[22:23], v[98:99], v[22:23] op_sel_hi:[0,1]
	v_exp_f32_e32 v72, v22
	v_exp_f32_e32 v74, v23
	v_pk_add_f32 v[22:23], v[92:93], v[160:161] op_sel_hi:[1,0]
	v_pk_add_f32 v[24:25], v[24:25], 1.0 op_sel_hi:[1,0]
	v_exp_f32_e32 v22, v22
	v_exp_f32_e32 v23, v23
	v_rcp_f32_e32 v24, v24
	v_rcp_f32_e32 v25, v25
	v_pk_add_f32 v[20:21], v[20:21], 1.0 op_sel_hi:[1,0]
	v_pk_add_f32 v[22:23], v[22:23], 1.0 op_sel_hi:[1,0]
	v_rcp_f32_e32 v20, v20
	v_rcp_f32_e32 v22, v22
	v_rcp_f32_e32 v23, v23
	v_pk_mul_f32 v[58:59], v[28:29], v[24:25]
	v_pk_add_f32 v[24:25], v[44:45], v[100:101] op_sel_hi:[1,0]
	v_rcp_f32_e32 v21, v21
	v_pk_mul_f32 v[22:23], v[156:157], v[22:23] op_sel_hi:[0,1]
	v_exp_f32_e32 v42, v22
	v_exp_f32_e32 v163, v23
	v_pk_add_f32 v[22:23], v[60:61], v[154:155] op_sel_hi:[1,0]
	v_exp_f32_e32 v24, v24
	v_exp_f32_e32 v22, v22
	v_exp_f32_e32 v23, v23
	v_exp_f32_e32 v25, v25
	v_pk_mul_f32 v[20:21], v[156:157], v[20:21] op_sel_hi:[0,1]
	v_exp_f32_e32 v40, v21
	v_pk_add_f32 v[22:23], v[22:23], 1.0 op_sel_hi:[1,0]
	v_pk_add_f32 v[24:25], v[24:25], 1.0 op_sel_hi:[1,0]
	v_rcp_f32_e32 v22, v22
	v_rcp_f32_e32 v23, v23
	v_rcp_f32_e32 v24, v24
	v_rcp_f32_e32 v25, v25
	v_exp_f32_e32 v20, v20
	v_pk_mul_f32 v[22:23], v[98:99], v[22:23] op_sel_hi:[0,1]
	v_exp_f32_e32 v22, v22
	v_exp_f32_e32 v23, v23
	v_pk_mul_f32 v[24:25], v[28:29], v[24:25]
	v_pk_add_f32 v[28:29], v[78:79], v[158:159] op_sel_hi:[1,0]
	v_mul_f32_e32 v90, v84, v67
	v_pk_fma_f32 v[26:27], v[22:23], v[22:23], 1.0 op_sel_hi:[1,1,0] neg_lo:[1,0,0] neg_hi:[1,0,0]
	v_exp_f32_e32 v28, v28
	v_sqrt_f32_e32 v26, v26
	v_sqrt_f32_e32 v27, v27
	v_exp_f32_e32 v29, v29
	v_mov_b32_e32 v78, v163
	v_exp_f32_e32 v200, v200
	v_pk_mul_f32 v[24:25], v[24:25], v[26:27]
	v_pk_add_f32 v[26:27], v[94:95], v[160:161] op_sel_hi:[1,0]
	v_pk_add_f32 v[28:29], v[28:29], 1.0 op_sel_hi:[1,0]
	v_exp_f32_e32 v26, v26
	v_exp_f32_e32 v27, v27
	v_rcp_f32_e32 v28, v28
	v_rcp_f32_e32 v29, v29
	v_fma_f32 v25, 0, v23, v25
	v_pk_add_f32 v[26:27], v[26:27], 1.0 op_sel_hi:[1,0]
	v_fmac_f32_e32 v24, v22, v25
	v_rcp_f32_e32 v26, v26
	v_rcp_f32_e32 v27, v27
	v_pk_mul_f32 v[44:45], v[30:31], v[28:29]
	v_pk_add_f32 v[28:29], v[46:47], v[100:101] op_sel_hi:[1,0]
	v_exp_f32_e32 v201, v201
	v_pk_mul_f32 v[26:27], v[156:157], v[26:27] op_sel_hi:[0,1]
	v_exp_f32_e32 v21, v26
	v_exp_f32_e32 v41, v27
	v_pk_add_f32 v[26:27], v[62:63], v[154:155] op_sel_hi:[1,0]
	v_exp_f32_e32 v28, v28
	v_exp_f32_e32 v26, v26
	v_exp_f32_e32 v27, v27
	v_exp_f32_e32 v29, v29
	v_pk_add_f32 v[200:201], v[200:201], 1.0 op_sel_hi:[1,0]
	v_pk_add_f32 v[26:27], v[26:27], 1.0 op_sel_hi:[1,0]
	s_nop 0
	v_rcp_f32_e32 v26, v26
	v_rcp_f32_e32 v27, v27
	v_pk_add_f32 v[28:29], v[28:29], 1.0 op_sel_hi:[1,0]
	v_rcp_f32_e32 v200, v200
	v_rcp_f32_e32 v28, v28
	v_rcp_f32_e32 v29, v29
	v_pk_mul_f32 v[26:27], v[98:99], v[26:27] op_sel_hi:[0,1]
	v_exp_f32_e32 v164, v26
	v_exp_f32_e32 v165, v27
	v_pk_mul_f32 v[28:29], v[30:31], v[28:29]
	v_pk_add_f32 v[30:31], v[80:81], v[158:159] op_sel_hi:[1,0]
	v_rcp_f32_e32 v201, v201
	v_pk_fma_f32 v[26:27], v[164:165], v[164:165], 1.0 op_sel_hi:[1,1,0] neg_lo:[1,0,0] neg_hi:[1,0,0]
	v_exp_f32_e32 v30, v30
	v_exp_f32_e32 v31, v31
	v_sqrt_f32_e32 v26, v26
	v_sqrt_f32_e32 v27, v27
	v_pk_mul_f32 v[2:3], v[2:3], v[200:201]
	v_pk_add_f32 v[30:31], v[30:31], 1.0 op_sel_hi:[1,0]
	v_pk_mul_f32 v[28:29], v[28:29], v[26:27]
	v_pk_add_f32 v[26:27], v[96:97], v[160:161] op_sel_hi:[1,0]
	v_rcp_f32_e32 v30, v30
	v_rcp_f32_e32 v31, v31
	v_exp_f32_e32 v26, v26
	v_exp_f32_e32 v27, v27
	v_pk_mul_f32 v[46:47], v[32:33], v[30:31]
	v_pk_add_f32 v[30:31], v[48:49], v[100:101] op_sel_hi:[1,0]
	v_pk_add_f32 v[26:27], v[26:27], 1.0 op_sel_hi:[1,0]
	v_exp_f32_e32 v30, v30
	v_exp_f32_e32 v31, v31
	v_rcp_f32_e32 v26, v26
	v_rcp_f32_e32 v27, v27
	v_mov_b32_e32 v100, v162
	v_pk_add_f32 v[30:31], v[30:31], 1.0 op_sel_hi:[1,0]
	v_pk_mul_f32 v[26:27], v[156:157], v[26:27] op_sel_hi:[0,1]
	v_rcp_f32_e32 v30, v30
	v_rcp_f32_e32 v31, v31
	v_exp_f32_e32 v43, v26
	v_exp_f32_e32 v79, v27
	v_pk_add_f32 v[26:27], v[64:65], v[154:155] op_sel_hi:[1,0]
	v_pk_mul_f32 v[30:31], v[32:33], v[30:31]
	v_exp_f32_e32 v26, v26
	v_exp_f32_e32 v27, v27
	ds_bpermute_b32 v32, v176, v51
	v_mul_f32_e32 v154, v85, v90
	v_mov_b32_e32 v91, v154
	v_pk_add_f32 v[26:27], v[26:27], 1.0 op_sel_hi:[1,0]
	s_waitcnt lgkmcnt(0)
	v_cndmask_b32_e64 v35, v32, v51, s[40:41]
	v_rcp_f32_e32 v26, v26
	v_rcp_f32_e32 v27, v27
	v_cndmask_b32_e64 v39, v51, v32, s[40:41]
	v_pk_fma_f32 v[32:33], v[100:101], v[100:101], 1.0 op_sel_hi:[1,1,0] neg_lo:[1,0,0] neg_hi:[1,0,0]
	ds_bpermute_b32 v100, v176, v154
	v_sqrt_f32_e32 v32, v32
	v_sqrt_f32_e32 v33, v33
	v_pk_mul_f32 v[26:27], v[98:99], v[26:27] op_sel_hi:[0,1]
	v_exp_f32_e32 v26, v26
	v_exp_f32_e32 v27, v27
	v_pk_mul_f32 v[88:89], v[88:89], v[32:33]
	v_mov_b32_e32 v32, v20
	v_mov_b32_e32 v33, v40
	v_pk_fma_f32 v[32:33], v[32:33], v[32:33], 1.0 op_sel_hi:[1,1,0] neg_lo:[1,0,0] neg_hi:[1,0,0]
	v_pk_fma_f32 v[48:49], v[26:27], v[26:27], 1.0 op_sel_hi:[1,1,0] neg_lo:[1,0,0] neg_hi:[1,0,0]
	v_sqrt_f32_e32 v32, v32
	v_sqrt_f32_e32 v33, v33
	v_sqrt_f32_e32 v48, v48
	v_sqrt_f32_e32 v49, v49
	v_fma_f32 v88, v162, v37, v88
	v_pk_mul_f32 v[76:77], v[166:167], v[32:33]
	v_mov_b32_e32 v32, v42
	v_mov_b32_e32 v33, v163
	v_pk_mul_f32 v[30:31], v[30:31], v[48:49]
	v_pk_fma_f32 v[32:33], v[32:33], v[32:33], 1.0 op_sel_hi:[1,1,0] neg_lo:[1,0,0] neg_hi:[1,0,0]
	v_mov_b32_e32 v48, v21
	v_mov_b32_e32 v49, v41
	v_sqrt_f32_e32 v32, v32
	v_sqrt_f32_e32 v33, v33
	v_pk_fma_f32 v[48:49], v[48:49], v[48:49], 1.0 op_sel_hi:[1,1,0] neg_lo:[1,0,0] neg_hi:[1,0,0]
	v_fma_f32 v76, 0, v20, v76
	v_sqrt_f32_e32 v48, v48
	v_sqrt_f32_e32 v49, v49
	v_pk_mul_f32 v[32:33], v[58:59], v[32:33]
	v_mov_b32_e32 v58, v43
	v_mov_b32_e32 v59, v79
	v_pk_mul_f32 v[48:49], v[44:45], v[48:49]
	v_pk_fma_f32 v[44:45], v[58:59], v[58:59], 1.0 op_sel_hi:[1,1,0] neg_lo:[1,0,0] neg_hi:[1,0,0]
	v_fmac_f32_e32 v77, v40, v76
	v_sqrt_f32_e32 v44, v44
	v_sqrt_f32_e32 v45, v45
	v_fma_f32 v57, v42, v77, v32
	v_pk_mul_f32 v[84:85], v[162:163], v[56:57]
	v_mov_b32_e32 v32, v101
	v_pk_mul_f32 v[80:81], v[46:47], v[44:45]
	v_fmac_f32_e32 v89, v101, v88
	v_pk_mul_f32 v[92:93], v[32:33], v[84:85]
	v_pk_fma_f32 v[62:63], v[162:163], v[56:57], v[32:33]
	v_fma_f32 v48, 0, v21, v48
	v_pk_mul_f32 v[46:47], v[20:21], v[40:41]
	ds_bpermute_b32 v62, v176, v92
	ds_bpermute_b32 v73, v176, v89
	v_fmac_f32_e32 v49, v41, v48
	v_pk_mul_f32 v[60:61], v[42:43], v[46:47]
	v_fma_f32 v41, v43, v49, v80
	v_mov_b32_e32 v40, v47
	v_pk_mul_f32 v[64:65], v[78:79], v[60:61]
	v_mov_b32_e32 v80, v79
	v_pk_mul_f32 v[32:33], v[58:59], v[40:41]
	ds_bpermute_b32 v61, v176, v64
	v_pk_fma_f32 v[42:43], v[58:59], v[40:41], v[80:81]
	ds_bpermute_b32 v75, v176, v63
	v_pk_mul_f32 v[44:45], v[80:81], v[32:33]
	s_waitcnt lgkmcnt(4)
	v_cndmask_b32_e64 v42, v100, v154, s[40:41]
	v_cndmask_b32_e64 v45, v154, v100, s[40:41]
	v_fmac_f32_e32 v35, 0, v42
	v_fmac_f32_e32 v39, v45, v35
	v_cndmask_b32_e64 v98, v35, 0, s[40:41]
	s_waitcnt lgkmcnt(2)
	v_cndmask_b32_e64 v35, v73, v89, s[40:41]
	v_cndmask_b32_e64 v58, v62, v92, s[40:41]
	v_cndmask_b32_e64 v42, v89, v73, s[40:41]
	v_fmac_f32_e32 v35, v58, v39
	v_cndmask_b32_e64 v78, v92, v62, s[40:41]
	v_fmac_f32_e32 v42, v78, v35
	s_waitcnt lgkmcnt(1)
	v_cndmask_b32_e64 v156, v61, v64, s[40:41]
	ds_bpermute_b32 v33, v176, v44
	s_waitcnt lgkmcnt(1)
	v_cndmask_b32_e64 v101, v75, v63, s[40:41]
	v_mul_f32_e32 v155, v156, v42
	ds_bpermute_b32 v40, v176, v43
	v_cndmask_b32_e64 v96, v100, 1.0, s[40:41]
	v_pk_mul_f32 v[80:81], v[154:155], v[100:101]
	v_pk_add_f32 v[100:101], v[154:155], v[100:101]
	v_cndmask_b32_e64 v59, v64, v61, s[40:41]
	v_mov_b32_e32 v81, v101
	v_cndmask_b32_e64 v79, v63, v75, s[40:41]
	v_pk_mul_f32 v[160:161], v[80:81], v[58:59]
	v_mov_b32_e32 v158, v59
	v_cndmask_b32_e64 v62, v160, v80, s[40:41]
	v_pk_mul_f32 v[160:161], v[78:79], v[160:161]
	v_pk_fma_f32 v[58:59], v[80:81], v[58:59], v[78:79]
	s_waitcnt lgkmcnt(1)
	v_cndmask_b32_e64 v157, v33, v65, s[40:41]
	v_mov_b32_e32 v161, v59
	s_waitcnt lgkmcnt(0)
	v_cndmask_b32_e64 v159, v40, v43, s[40:41]
	v_cndmask_b32_e64 v80, v101, v42, s[40:41]
	v_pk_mul_f32 v[100:101], v[156:157], v[160:161]
	v_pk_fma_f32 v[156:157], v[156:157], v[160:161], v[158:159]
	v_pk_mul_f32 v[166:167], v[158:159], v[100:101]
	v_cndmask_b32_e64 v79, v44, v33, s[40:41]
	v_cndmask_b32_e64 v78, v33, v44, s[40:41]
	v_mov_b32_e32 v167, v157
	v_cndmask_b32_e64 v163, v43, v40, s[40:41]
	v_mov_b32_e32 v162, v79
	v_pk_mul_f32 v[158:159], v[78:79], v[166:167]
	v_cndmask_b32_e64 v58, v157, v59, s[40:41]
	v_pk_fma_f32 v[156:157], v[150:151], v[150:151], 1.0 op_sel_hi:[1,1,0] neg_lo:[1,0,0] neg_hi:[1,0,0]
	v_cndmask_b32_e64 v42, v100, v160, s[40:41]
	v_pk_mul_f32 v[100:101], v[162:163], v[158:159]
	v_cndmask_b32_e64 v40, v158, v166, s[40:41]
	v_sqrt_f32_e32 v158, v157
	v_sqrt_f32_e32 v159, v156
	v_mov_b32_e32 v73, v74
	v_fma_f32 v31, 0, v27, v31
	v_fmac_f32_e32 v30, v26, v31
	v_pk_mul_f32 v[158:159], v[152:153], v[158:159]
	v_mov_b32_e32 v152, v53
	v_mov_b32_e32 v153, v19
	v_pk_fma_f32 v[152:153], v[152:153], v[152:153], 1.0 op_sel_hi:[1,1,0] neg_lo:[1,0,0] neg_hi:[1,0,0]
	v_mul_f32_e32 v26, v27, v26
	v_sqrt_f32_e32 v152, v152
	v_sqrt_f32_e32 v153, v153
	v_cndmask_b32_e64 v94, v35, v39, s[40:41]
	v_pk_fma_f32 v[78:79], v[78:79], v[166:167], v[162:163]
	v_fma_f32 v29, v165, v30, v29
	v_pk_mul_f32 v[168:169], v[68:69], v[152:153]
	v_mov_b32_e32 v68, v146
	v_mov_b32_e32 v69, v38
	v_pk_fma_f32 v[68:69], v[68:69], v[68:69], 1.0 op_sel_hi:[1,1,0] neg_lo:[1,0,0] neg_hi:[1,0,0]
	v_fma_f32 v169, 0, v19, v169
	v_sqrt_f32_e32 v68, v68
	v_sqrt_f32_e32 v69, v69
	v_fmac_f32_e32 v168, v53, v169
	v_pk_mul_f32 v[152:153], v[18:19], v[52:53]
	v_mul_f32_e32 v33, v165, v26
	v_pk_mul_f32 v[54:55], v[54:55], v[68:69]
	v_mov_b32_e32 v68, v52
	v_mov_b32_e32 v69, v18
	v_pk_fma_f32 v[68:69], v[68:69], v[68:69], 1.0 op_sel_hi:[1,1,0] neg_lo:[1,0,0] neg_hi:[1,0,0]
	v_mov_b32_e32 v39, v150
	v_sqrt_f32_e32 v68, v68
	v_sqrt_f32_e32 v69, v69
	v_fma_f32 v163, v150, v168, v159
	v_mov_b32_e32 v162, v153
	v_mov_b32_e32 v101, v79
	v_pk_mul_f32 v[156:157], v[70:71], v[68:69]
	v_pk_fma_f32 v[68:69], v[72:73], v[72:73], 1.0 op_sel_hi:[1,1,0] neg_lo:[1,0,0] neg_hi:[1,0,0]
	v_fma_f32 v157, 0, v18, v157
	v_sqrt_f32_e32 v68, v68
	v_sqrt_f32_e32 v69, v69
	v_fmac_f32_e32 v156, v52, v157
	v_mul_f32_e32 v78, v23, v22
	v_fmac_f32_e32 v28, v164, v29
	v_mov_b32_e32 v75, v146
	v_pk_mul_f32 v[86:87], v[86:87], v[68:69]
	v_pk_mul_f32 v[184:185], v[150:151], v[162:163]
	v_pk_mul_f32 v[166:167], v[38:39], v[152:153]
	v_pk_mov_b32 v[68:69], v[150:151], v[158:159] op_sel:[1,0]
	v_fma_f32 v79, v38, v156, v55
	v_mul_f32_e32 v38, v164, v33
	ds_bpermute_b32 v22, v176, v28
	v_pk_mul_f32 v[172:173], v[68:69], v[184:185]
	v_pk_fma_f32 v[68:69], v[150:151], v[162:163], v[68:69]
	v_pk_mul_f32 v[150:151], v[74:75], v[78:79]
	v_mov_b32_e32 v73, v54
	v_fma_f32 v87, v74, v24, v87
	ds_bpermute_b32 v54, v176, v38
	v_pk_mul_f32 v[70:71], v[72:73], v[150:151]
	v_fmac_f32_e32 v86, v72, v87
	ds_bpermute_b32 v61, v176, v70
	ds_bpermute_b32 v65, v176, v86
	v_pk_mul_f32 v[158:159], v[146:147], v[166:167]
	ds_bpermute_b32 v39, v176, v158
	v_pk_fma_f32 v[52:53], v[74:75], v[78:79], v[72:73]
	s_waitcnt lgkmcnt(4)
	v_cndmask_b32_e64 v35, v22, v28, s[40:41]
	v_cndmask_b32_e64 v22, v28, v22, s[40:41]
	ds_bpermute_b32 v55, v176, v53
	s_waitcnt lgkmcnt(4)
	v_cndmask_b32_e64 v68, v38, v54, s[40:41]
	v_cndmask_b32_e64 v52, v54, v38, s[40:41]
	v_fmac_f32_e32 v22, 0, v68
	v_fmac_f32_e32 v35, v52, v22
	s_waitcnt lgkmcnt(2)
	v_cndmask_b32_e64 v71, v65, v86, s[40:41]
	v_cndmask_b32_e64 v65, v86, v65, s[40:41]
	v_cndmask_b32_e64 v72, v70, v61, s[40:41]
	v_fmac_f32_e32 v65, v72, v35
	v_cndmask_b32_e64 v146, v61, v70, s[40:41]
	v_fmac_f32_e32 v71, v146, v65
	s_waitcnt lgkmcnt(1)
	v_cndmask_b32_e64 v186, v158, v39, s[40:41]
	ds_bpermute_b32 v45, v176, v172
	v_cndmask_b32_e64 v73, v39, v158, s[40:41]
	s_waitcnt lgkmcnt(1)
	v_cndmask_b32_e64 v147, v55, v53, s[40:41]
	v_cndmask_b32_e64 v55, v53, v55, s[40:41]
	v_mul_f32_e32 v39, v186, v71
	ds_bpermute_b32 v59, v176, v69
	v_cndmask_b32_e64 v52, 0, v22, s[40:41]
	v_cndmask_b32_e64 v22, 1.0, v54, s[40:41]
	v_pk_mul_f32 v[160:161], v[38:39], v[54:55]
	v_pk_add_f32 v[54:55], v[38:39], v[54:55]
	v_mov_b32_e32 v188, v73
	v_mov_b32_e32 v161, v55
	v_pk_mul_f32 v[164:165], v[160:161], v[72:73]
	v_pk_fma_f32 v[72:73], v[160:161], v[72:73], v[146:147]
	v_pk_mul_f32 v[190:191], v[146:147], v[164:165]
	s_waitcnt lgkmcnt(1)
	v_cndmask_b32_e64 v187, v159, v45, s[40:41]
	v_mov_b32_e32 v191, v73
	s_waitcnt lgkmcnt(0)
	v_cndmask_b32_e64 v189, v69, v59, s[40:41]
	v_pk_mul_f32 v[146:147], v[186:187], v[190:191]
	v_pk_fma_f32 v[186:187], v[186:187], v[190:191], v[188:189]
	v_pk_mul_f32 v[194:195], v[188:189], v[146:147]
	v_cndmask_b32_e64 v68, v160, v164, s[40:41]
	v_cndmask_b32_e64 v164, v71, v55, s[40:41]
	v_cndmask_b32_e64 v55, v45, v172, s[40:41]
	v_cndmask_b32_e64 v54, v172, v45, s[40:41]
	v_mov_b32_e32 v195, v187
	v_cndmask_b32_e64 v193, v59, v69, s[40:41]
	v_mov_b32_e32 v192, v55
	v_pk_mul_f32 v[188:189], v[54:55], v[194:195]
	v_cndmask_b32_e64 v160, v190, v146, s[40:41]
	v_pk_mul_f32 v[190:191], v[192:193], v[188:189]
	v_pk_fma_f32 v[146:147], v[54:55], v[194:195], v[192:193]
	v_pk_mul_f32 v[192:193], v[4:5], v[4:5]
	v_cndmask_b32_e64 v186, v73, v187, s[40:41]
	v_pk_mul_f32 v[192:193], v[4:5], v[192:193]
	v_mov_b32_e32 v173, v184
	v_pk_fma_f32 v[154:155], v[192:193], s[54:55], v[4:5] op_sel_hi:[1,0,1]
	v_mov_b32_e32 v162, v69
	v_pk_mul_f32 v[154:155], v[154:155], s[28:29] op_sel_hi:[1,0]
	v_mov_b32_e32 v146, v190
	v_exp_f32_e32 v154, v154
	v_exp_f32_e32 v155, v155
	v_cndmask_b32_e64 v188, v194, v188, s[40:41]
	v_pk_fma_f32 v[184:185], v[66:67], v[98:99], v[82:83] op_sel_hi:[1,0,1]
	v_pk_fma_f32 v[190:191], v[172:173], v[186:187], v[162:163] op_sel_hi:[1,0,1]
	v_pk_mul_f32 v[66:67], v[96:97], v[66:67] op_sel_hi:[0,1]
	v_pk_add_f32 v[184:185], v[184:185], v[190:191]
	v_pk_mul_f32 v[172:173], v[172:173], v[188:189] op_sel_hi:[1,0]
	v_pk_mul_f32 v[184:185], v[2:3], v[184:185]
	v_pk_mul_f32 v[66:67], v[2:3], v[66:67]
	v_pk_mul_f32 v[2:3], v[2:3], v[172:173]
	v_pk_add_f32 v[154:155], v[154:155], 1.0 op_sel_hi:[1,0]
	v_cndmask_b32_e64 v74, v35, v65, s[40:41]
	v_lshlrev_b32_e32 v35, 1, v170
	v_cvt_pk_bf16_f32 v2, v2, v3
	v_mul_lo_u32 v3, v177, s0
	v_rcp_f32_e32 v154, v154
	v_rcp_f32_e32 v155, v155
	v_cvt_pk_bf16_f32 v39, v184, v185
	v_add3_u32 v161, s75, v35, v3
	v_cvt_pk_bf16_f32 v45, v66, v67
	ds_write_b16 v161, v39 offset:49152
	ds_write_b16_d16_hi v161, v39 offset:49232
	ds_write_b16 v161, v45 offset:51712
	ds_write_b16_d16_hi v161, v45 offset:51792
	ds_write_b16 v161, v2 offset:54272
	ds_write_b16_d16_hi v161, v2 offset:54352
	v_mov_b32_e32 v2, v153
	v_mov_b32_e32 v3, v19
	v_pk_fma_f32 v[50:51], v[90:91], v[98:99], v[50:51] op_sel_hi:[1,0,1]
	v_pk_fma_f32 v[66:67], v[2:3], v[186:187], v[168:169] op_sel_hi:[1,0,1]
	v_pk_mul_f32 v[4:5], v[4:5], v[154:155]
	v_pk_add_f32 v[50:51], v[50:51], v[66:67]
	v_pk_mul_f32 v[2:3], v[2:3], v[188:189] op_sel_hi:[1,0]
	v_pk_mul_f32 v[194:195], v[6:7], v[6:7]
	v_pk_mul_f32 v[50:51], v[4:5], v[50:51]
	v_pk_mul_f32 v[66:67], v[96:97], v[90:91] op_sel_hi:[0,1]
	v_pk_mul_f32 v[2:3], v[4:5], v[2:3]
	v_pk_mul_f32 v[194:195], v[6:7], v[194:195]
	v_pk_mul_f32 v[66:67], v[4:5], v[66:67]
	v_cvt_pk_bf16_f32 v4, v50, v51
	v_cvt_pk_bf16_f32 v2, v2, v3
	v_mov_b32_e32 v35, v56
	v_cvt_pk_bf16_f32 v5, v66, v67
	ds_write_b16 v161, v4 offset:49312
	ds_write_b16_d16_hi v161, v4 offset:49392
	ds_write_b16 v161, v5 offset:51872
	ds_write_b16_d16_hi v161, v5 offset:51952
	ds_write_b16 v161, v2 offset:54432
	ds_write_b16_d16_hi v161, v2 offset:54512
	v_pk_fma_f32 v[2:3], v[34:35], v[94:95], v[36:37] op_sel_hi:[1,0,1]
	v_pk_fma_f32 v[36:37], v[194:195], s[54:55], v[6:7] op_sel_hi:[1,0,1]
	v_mov_b32_e32 v159, v166
	v_pk_mul_f32 v[36:37], v[36:37], s[28:29] op_sel_hi:[1,0]
	v_mov_b32_e32 v4, v53
	v_exp_f32_e32 v36, v36
	v_exp_f32_e32 v37, v37
	v_mov_b32_e32 v5, v79
	v_pk_fma_f32 v[4:5], v[158:159], v[164:165], v[4:5] op_sel_hi:[1,0,1]
	v_pk_mul_f32 v[170:171], v[8:9], v[8:9]
	v_pk_add_f32 v[36:37], v[36:37], 1.0 op_sel_hi:[1,0]
	v_pk_add_f32 v[2:3], v[2:3], v[4:5]
	v_rcp_f32_e32 v36, v36
	v_rcp_f32_e32 v37, v37
	v_pk_mul_f32 v[4:5], v[34:35], v[62:63] op_sel_hi:[1,0]
	v_pk_mul_f32 v[34:35], v[158:159], v[160:161] op_sel_hi:[1,0]
	v_pk_mul_f32 v[170:171], v[8:9], v[170:171]
	v_pk_mul_f32 v[6:7], v[6:7], v[36:37]
	v_mov_b32_e32 v85, v92
	v_pk_mul_f32 v[2:3], v[6:7], v[2:3]
	v_pk_mul_f32 v[4:5], v[6:7], v[4:5]
	v_pk_mul_f32 v[6:7], v[6:7], v[34:35]
	v_cvt_pk_bf16_f32 v2, v2, v3
	v_cvt_pk_bf16_f32 v3, v4, v5
	v_cvt_pk_bf16_f32 v4, v6, v7
	v_pk_fma_f32 v[6:7], v[170:171], s[54:55], v[8:9] op_sel_hi:[1,0,1]
	v_mov_b32_e32 v153, v18
	v_pk_mul_f32 v[6:7], v[6:7], s[28:29] op_sel_hi:[1,0]
	v_pk_mul_f32 v[162:163], v[10:11], v[10:11]
	v_exp_f32_e32 v6, v6
	v_exp_f32_e32 v7, v7
	ds_write_b16 v161, v2 offset:49792
	ds_write_b16_d16_hi v161, v2 offset:49872
	ds_write_b16 v161, v3 offset:52352
	ds_write_b16_d16_hi v161, v3 offset:52432
	ds_write_b16 v161, v4 offset:54912
	ds_write_b16_d16_hi v161, v4 offset:54992
	v_pk_fma_f32 v[2:3], v[84:85], v[94:95], v[88:89] op_sel_hi:[1,0,1]
	v_pk_fma_f32 v[4:5], v[152:153], v[164:165], v[156:157] op_sel_hi:[1,0,1]
	v_pk_add_f32 v[6:7], v[6:7], 1.0 op_sel_hi:[1,0]
	v_pk_mul_f32 v[162:163], v[10:11], v[162:163]
	v_rcp_f32_e32 v6, v6
	v_rcp_f32_e32 v7, v7
	v_pk_add_f32 v[2:3], v[2:3], v[4:5]
	v_pk_mul_f32 v[4:5], v[84:85], v[62:63] op_sel_hi:[1,0]
	v_mov_b32_e32 v71, v150
	v_pk_mul_f32 v[6:7], v[8:9], v[6:7]
	v_pk_mul_f32 v[8:9], v[152:153], v[160:161] op_sel_hi:[1,0]
	v_pk_mul_f32 v[2:3], v[6:7], v[2:3]
	v_pk_mul_f32 v[4:5], v[6:7], v[4:5]
	v_pk_mul_f32 v[6:7], v[6:7], v[8:9]
	v_pk_fma_f32 v[8:9], v[162:163], s[54:55], v[10:11] op_sel_hi:[1,0,1]
	v_cvt_pk_bf16_f32 v2, v2, v3
	v_pk_mul_f32 v[8:9], v[8:9], s[28:29] op_sel_hi:[1,0]
	v_cvt_pk_bf16_f32 v3, v4, v5
	v_exp_f32_e32 v8, v8
	v_exp_f32_e32 v9, v9
	v_cvt_pk_bf16_f32 v4, v6, v7
	ds_write_b16 v161, v2 offset:49952
	ds_write_b16_d16_hi v161, v2 offset:50032
	ds_write_b16 v161, v3 offset:52512
	ds_write_b16_d16_hi v161, v3 offset:52592
	ds_write_b16 v161, v4 offset:55072
	ds_write_b16_d16_hi v161, v4 offset:55152
	v_mov_b32_e32 v2, v20
	v_pk_add_f32 v[8:9], v[8:9], 1.0 op_sel_hi:[1,0]
	v_mov_b32_e32 v3, v46
	v_rcp_f32_e32 v8, v8
	v_rcp_f32_e32 v9, v9
	v_pk_fma_f32 v[4:5], v[2:3], v[80:81], v[76:77] op_sel_hi:[1,0,1]
	v_pk_fma_f32 v[6:7], v[70:71], v[74:75], v[86:87] op_sel_hi:[1,0,1]
	v_pk_mul_f32 v[82:83], v[12:13], v[12:13]
	v_pk_mul_f32 v[8:9], v[10:11], v[8:9]
	v_pk_add_f32 v[4:5], v[6:7], v[4:5]
	v_pk_mul_f32 v[2:3], v[2:3], v[42:43] op_sel_hi:[1,0]
	v_pk_mul_f32 v[6:7], v[70:71], v[68:69] op_sel_hi:[1,0]
	v_pk_mul_f32 v[82:83], v[12:13], v[82:83]
	v_pk_mul_f32 v[2:3], v[8:9], v[2:3]
	v_pk_mul_f32 v[6:7], v[8:9], v[6:7]
	v_cvt_pk_bf16_f32 v2, v2, v3
	v_cvt_pk_bf16_f32 v3, v6, v7
	v_pk_fma_f32 v[6:7], v[82:83], s[54:55], v[12:13] op_sel_hi:[1,0,1]
	v_pk_mul_f32 v[4:5], v[8:9], v[4:5]
	v_pk_mul_f32 v[6:7], v[6:7], s[28:29] op_sel_hi:[1,0]
	v_cvt_pk_bf16_f32 v4, v4, v5
	v_exp_f32_e32 v6, v6
	v_exp_f32_e32 v7, v7
	v_mov_b32_e32 v61, v64
	v_mov_b32_e32 v79, v23
	v_mov_b32_e32 v62, v57
	v_pk_add_f32 v[6:7], v[6:7], 1.0 op_sel_hi:[1,0]
	ds_write_b16 v161, v4 offset:50432
	ds_write_b16_d16_hi v161, v4 offset:50512
	ds_write_b16 v161, v2 offset:52992
	ds_write_b16_d16_hi v161, v2 offset:53072
	ds_write_b16 v161, v3 offset:55552
	ds_write_b16_d16_hi v161, v3 offset:55632
	v_rcp_f32_e32 v6, v6
	v_rcp_f32_e32 v7, v7
	v_pk_fma_f32 v[2:3], v[60:61], v[80:81], v[62:63] op_sel_hi:[1,0,1]
	v_pk_fma_f32 v[4:5], v[78:79], v[74:75], v[24:25] op_sel_hi:[1,0,1]
	v_pk_mul_f32 v[72:73], v[14:15], v[14:15]
	v_pk_mul_f32 v[6:7], v[12:13], v[6:7]
	v_pk_add_f32 v[2:3], v[4:5], v[2:3]
	v_pk_mul_f32 v[4:5], v[60:61], v[42:43] op_sel_hi:[1,0]
	v_pk_mul_f32 v[8:9], v[78:79], v[68:69] op_sel_hi:[1,0]
	v_pk_mul_f32 v[72:73], v[14:15], v[72:73]
	v_pk_mul_f32 v[2:3], v[6:7], v[2:3]
	v_pk_mul_f32 v[4:5], v[6:7], v[4:5]
	v_pk_mul_f32 v[6:7], v[6:7], v[8:9]
	v_cvt_pk_bf16_f32 v2, v2, v3
	v_cvt_pk_bf16_f32 v3, v4, v5
	v_cvt_pk_bf16_f32 v4, v6, v7
	v_pk_fma_f32 v[6:7], v[72:73], s[54:55], v[14:15] op_sel_hi:[1,0,1]
	v_mov_b32_e32 v46, v21
	v_pk_mul_f32 v[6:7], v[6:7], s[28:29] op_sel_hi:[1,0]
	v_mov_b32_e32 v39, v33
	v_exp_f32_e32 v6, v6
	v_exp_f32_e32 v7, v7
	ds_write_b16 v161, v2 offset:50592
	ds_write_b16_d16_hi v161, v2 offset:50672
	ds_write_b16 v161, v3 offset:53152
	ds_write_b16_d16_hi v161, v3 offset:53232
	ds_write_b16 v161, v4 offset:55712
	ds_write_b16_d16_hi v161, v4 offset:55792
	v_pk_fma_f32 v[2:3], v[46:47], v[58:59], v[48:49] op_sel_hi:[1,0,1]
	v_pk_fma_f32 v[4:5], v[38:39], v[52:53], v[28:29] op_sel_hi:[1,0,1]
	v_pk_add_f32 v[6:7], v[6:7], 1.0 op_sel_hi:[1,0]
	v_pk_mul_f32 v[54:55], v[16:17], v[16:17]
	v_rcp_f32_e32 v6, v6
	v_rcp_f32_e32 v7, v7
	v_pk_add_f32 v[2:3], v[4:5], v[2:3]
	v_pk_mul_f32 v[4:5], v[46:47], v[40:41] op_sel_hi:[1,0]
	v_pk_mul_f32 v[8:9], v[38:39], v[22:23] op_sel_hi:[1,0]
	v_pk_mul_f32 v[6:7], v[14:15], v[6:7]
	v_pk_mul_f32 v[54:55], v[16:17], v[54:55]
	v_pk_mul_f32 v[2:3], v[6:7], v[2:3]
	v_pk_mul_f32 v[4:5], v[6:7], v[4:5]
	v_pk_mul_f32 v[6:7], v[6:7], v[8:9]
	v_cvt_pk_bf16_f32 v2, v2, v3
	v_cvt_pk_bf16_f32 v3, v4, v5
	v_cvt_pk_bf16_f32 v4, v6, v7
	v_pk_fma_f32 v[6:7], v[54:55], s[54:55], v[16:17] op_sel_hi:[1,0,1]
	v_mov_b32_e32 v33, v44
	v_pk_mul_f32 v[6:7], v[6:7], s[28:29] op_sel_hi:[1,0]
	v_mov_b32_e32 v42, v41
	v_exp_f32_e32 v6, v6
	v_exp_f32_e32 v7, v7
	ds_write_b16 v161, v2 offset:51072
	ds_write_b16_d16_hi v161, v2 offset:51152
	ds_write_b16 v161, v3 offset:53632
	ds_write_b16_d16_hi v161, v3 offset:53712
	ds_write_b16 v161, v4 offset:56192
	ds_write_b16_d16_hi v161, v4 offset:56272
	v_pk_fma_f32 v[2:3], v[32:33], v[58:59], v[42:43] op_sel_hi:[1,0,1]
	v_pk_fma_f32 v[4:5], v[26:27], v[52:53], v[30:31] op_sel_hi:[1,0,1]
	v_pk_add_f32 v[6:7], v[6:7], 1.0 op_sel_hi:[1,0]
	v_pk_add_f32 v[2:3], v[4:5], v[2:3]
	v_rcp_f32_e32 v6, v6
	v_rcp_f32_e32 v7, v7
	v_pk_mul_f32 v[4:5], v[32:33], v[40:41] op_sel_hi:[1,0]
	v_pk_mul_f32 v[8:9], v[26:27], v[22:23] op_sel_hi:[1,0]
	v_add3_u32 v160, s75, v181, v182
	v_pk_mul_f32 v[6:7], v[16:17], v[6:7]
	v_lshlrev_b64 v[26:27], 1, v[148:149]
	v_pk_mul_f32 v[2:3], v[6:7], v[2:3]
	v_pk_mul_f32 v[4:5], v[6:7], v[4:5]
	v_pk_mul_f32 v[6:7], v[6:7], v[8:9]
	v_cvt_pk_bf16_f32 v2, v2, v3
	v_cvt_pk_bf16_f32 v3, v4, v5
	v_cvt_pk_bf16_f32 v4, v6, v7
	ds_write_b16 v161, v2 offset:51232
	ds_write_b16_d16_hi v161, v2 offset:51312
	ds_write_b16 v161, v3 offset:53792
	ds_write_b16_d16_hi v161, v3 offset:53872
	ds_write_b16 v161, v4 offset:56352
	ds_write_b16_d16_hi v161, v4 offset:56432
	s_waitcnt lgkmcnt(0)
	ds_read_b128 v[2:5], v160 offset:49152
	ds_read_b128 v[6:9], v160 offset:49168
	ds_read_b128 v[10:13], v160 offset:51712
	ds_read_b128 v[14:17], v160 offset:51728
	ds_read_b128 v[18:21], v160 offset:54272
	ds_read_b128 v[22:25], v160 offset:54288
	s_waitcnt lgkmcnt(0)
	v_lshl_add_u64 v[148:149], s[22:23], 0, v[26:27]
	s_waitcnt lgkmcnt(5)
	global_store_dwordx4 v[148:149], v[2:5], off
	s_brev_b32 s0, 32
	v_lshl_add_u64 v[152:153], s[34:35], 0, v[26:27]
	v_lshl_add_u64 v[2:3], s[46:47], 0, v[26:27]
	v_add_co_u32_e32 v150, vcc, s0, v2
	s_mov_b32 s0, 0x6000000
	s_nop 0
	v_addc_co_u32_e32 v151, vcc, 0, v3, vcc
	v_add_co_u32_e32 v154, vcc, s0, v2
	s_mov_b32 s0, 0x12000000
	s_nop 0
	v_addc_co_u32_e32 v155, vcc, 0, v3, vcc
	v_add_co_u32_e32 v158, vcc, s0, v2
	v_lshl_add_u64 v[156:157], s[84:85], 0, v[26:27]
	s_nop 0
	v_addc_co_u32_e32 v159, vcc, 0, v3, vcc
	s_waitcnt lgkmcnt(4)
	global_store_dwordx4 v[150:151], v[6:9], off offset:16
	s_waitcnt lgkmcnt(3)
	global_store_dwordx4 v[152:153], v[10:13], off
	s_waitcnt lgkmcnt(2)
	global_store_dwordx4 v[154:155], v[14:17], off offset:16
	s_waitcnt lgkmcnt(1)
	global_store_dwordx4 v[156:157], v[18:21], off
	s_waitcnt lgkmcnt(0)
	global_store_dwordx4 v[158:159], v[22:25], off offset:16
	ds_read_b128 v[202:205], v179 offset:4608
	ds_read_b128 v[206:209], v179 offset:13824
	ds_read_b128 v[210:213], v179 offset:23040
	ds_read_b128 v[214:217], v179 offset:32256
	ds_read_b128 v[218:221], v179 offset:41472
	ds_read_b128 v[222:225], v179 offset:13856
	ds_read_b128 v[238:241], v179 offset:23072
	ds_read_b128 v[242:245], v179 offset:32288
	ds_read_b128 v[162:165], v179 offset:4640
	s_nop 0
	s_waitcnt lgkmcnt(8)
	v_mfma_f32_32x32x16_bf16 v[82:97], v[122:125], v[202:205], 0
	ds_read_b128 v[202:205], v179 offset:41504
	v_add_u32_e32 v98, 0x80, v178
	s_waitcnt lgkmcnt(8)
	v_mfma_f32_32x32x16_bf16 v[66:81], v[122:125], v[206:209], 0
	ds_read_b128 v[206:209], v179 offset:4672
	s_waitcnt lgkmcnt(8)
	v_mfma_f32_32x32x16_bf16 v[50:65], v[122:125], v[210:213], 0
	ds_read_b128 v[210:213], v179 offset:13888
	s_waitcnt lgkmcnt(8)
	v_mfma_f32_32x32x16_bf16 v[34:49], v[122:125], v[214:217], 0
	ds_read_b128 v[214:217], v179 offset:23104
	s_waitcnt lgkmcnt(8)
	v_mfma_f32_32x32x16_bf16 v[18:33], v[122:125], v[218:221], 0
	v_mfma_f32_32x32x16_bf16 v[2:17], v[114:117], v[218:221], 0
	ds_read_b128 v[218:221], v179 offset:32320
	s_waitcnt lgkmcnt(8)
	v_mfma_f32_32x32x16_bf16 v[66:81], v[126:129], v[222:225], v[66:81]
	ds_read_b128 v[222:225], v179 offset:41536
	s_waitcnt lgkmcnt(8)
	v_mfma_f32_32x32x16_bf16 v[50:65], v[126:129], v[238:241], v[50:65]
	ds_read_b128 v[238:241], v179 offset:4704
	s_waitcnt lgkmcnt(8)
	v_mfma_f32_32x32x16_bf16 v[34:49], v[126:129], v[242:245], v[34:49]
	ds_read_b128 v[242:245], v179 offset:13920
	s_waitcnt lgkmcnt(8)
	v_mfma_f32_32x32x16_bf16 v[82:97], v[126:129], v[162:165], v[82:97]
	ds_read_b128 v[162:165], v179 offset:23136
	s_waitcnt lgkmcnt(8)
	v_mfma_f32_32x32x16_bf16 v[2:17], v[110:113], v[202:205], v[2:17]
	s_nop 0
	s_waitcnt lgkmcnt(7)
	v_mfma_f32_32x32x16_bf16 v[82:97], v[130:133], v[206:209], v[82:97]
	ds_read_b128 v[206:209], v179 offset:32352
	s_waitcnt lgkmcnt(7)
	v_mfma_f32_32x32x16_bf16 v[66:81], v[130:133], v[210:213], v[66:81]
	ds_read_b128 v[210:213], v179 offset:41568
	s_waitcnt lgkmcnt(7)
	v_mfma_f32_32x32x16_bf16 v[50:65], v[130:133], v[214:217], v[50:65]
	s_nop 0
	s_waitcnt lgkmcnt(6)
	v_mfma_f32_32x32x16_bf16 v[34:49], v[130:133], v[218:221], v[34:49]
	s_nop 0
	s_waitcnt lgkmcnt(5)
	v_mfma_f32_32x32x16_bf16 v[2:17], v[106:109], v[222:225], v[2:17]
	s_nop 0
	s_waitcnt lgkmcnt(4)
	v_mfma_f32_32x32x16_bf16 v[82:97], v[118:121], v[238:241], v[82:97]
	s_nop 0
	s_waitcnt lgkmcnt(3)
	v_mfma_f32_32x32x16_bf16 v[66:81], v[118:121], v[242:245], v[66:81]
	s_nop 0
	v_mfma_f32_32x32x16_bf16 v[18:33], v[126:129], v[202:205], v[18:33]
	s_waitcnt lgkmcnt(2)
	v_mfma_f32_32x32x16_bf16 v[50:65], v[118:121], v[162:165], v[50:65]
	s_nop 0
	v_mfma_f32_32x32x16_bf16 v[18:33], v[130:133], v[222:225], v[18:33]
	s_waitcnt lgkmcnt(1)
	v_mfma_f32_32x32x16_bf16 v[34:49], v[118:121], v[206:209], v[34:49]
	s_nop 0
	ds_read2st64_b32 v[116:117], v98 offset0:185 offset1:186
	ds_read2st64_b32 v[110:111], v98 offset0:187 offset1:188
	ds_read2st64_b32 v[112:113], v98 offset0:189 offset1:190
	s_waitcnt lgkmcnt(2)
	v_mov_b32_e32 v114, v117
	v_pk_add_f32 v[66:67], v[66:67], v[114:115] op_sel_hi:[1,0]
	v_pk_add_f32 v[82:83], v[82:83], v[116:117] op_sel_hi:[1,0]
	v_mfma_f32_32x32x16_bf16 v[18:33], v[118:121], v[210:213], v[18:33]
	v_exp_f32_e32 v66, v66
	v_exp_f32_e32 v67, v67
	v_exp_f32_e32 v82, v82
	v_exp_f32_e32 v83, v83
	s_waitcnt lgkmcnt(1)
	v_pk_add_f32 v[50:51], v[50:51], v[110:111] op_sel_hi:[1,0]
	v_pk_add_f32 v[66:67], v[66:67], 1.0 op_sel_hi:[1,0]
	v_exp_f32_e32 v50, v50
	v_mfma_f32_32x32x16_bf16 v[2:17], v[102:105], v[210:213], v[2:17]
	v_mov_b32_e32 v108, v111
	v_add_f32_e64 v34, v34, v108
	v_add_f32_e64 v35, v35, v108
	v_rcp_f32_e32 v102, v66
	v_exp_f32_e32 v34, v34
	v_exp_f32_e32 v35, v35
	v_rcp_f32_e32 v103, v67
	v_pk_add_f32 v[82:83], v[82:83], 1.0 op_sel_hi:[1,0]
	v_exp_f32_e32 v51, v51
	v_pk_add_f32 v[34:35], v[34:35], 1.0 op_sel_hi:[1,0]
	v_pk_mul_f32 v[102:103], v[18:19], v[102:103]
	v_rcp_f32_e32 v34, v34
	v_rcp_f32_e32 v35, v35
	v_rcp_f32_e32 v82, v82
	v_rcp_f32_e32 v83, v83
	v_pk_add_f32 v[50:51], v[50:51], 1.0 op_sel_hi:[1,0]
	v_pk_mul_f32 v[106:107], v[18:19], v[34:35]
	v_pk_add_f32 v[18:19], v[84:85], v[116:117] op_sel_hi:[1,0]
	v_pk_add_f32 v[34:35], v[68:69], v[114:115] op_sel_hi:[1,0]
	v_exp_f32_e32 v18, v18
	v_exp_f32_e32 v19, v19
	s_waitcnt lgkmcnt(0)
	v_pk_mul_f32 v[66:67], v[112:113], v[82:83] op_sel_hi:[0,1]
	v_exp_f32_e32 v34, v34
	v_exp_f32_e32 v35, v35
	v_pk_add_f32 v[18:19], v[18:19], 1.0 op_sel_hi:[1,0]
	v_exp_f32_e32 v66, v66
	v_rcp_f32_e32 v18, v18
	v_rcp_f32_e32 v19, v19
	v_exp_f32_e32 v67, v67
	v_pk_add_f32 v[34:35], v[34:35], 1.0 op_sel_hi:[1,0]
	v_rcp_f32_e32 v50, v50
	v_pk_mul_f32 v[18:19], v[112:113], v[18:19] op_sel_hi:[0,1]
	v_exp_f32_e32 v84, v18
	v_exp_f32_e32 v85, v19
	v_pk_fma_f32 v[82:83], v[66:67], v[66:67], 1.0 op_sel_hi:[1,1,0] neg_lo:[1,0,0] neg_hi:[1,0,0]
	v_rcp_f32_e32 v51, v51
	v_rcp_f32_e32 v34, v34
	v_rcp_f32_e32 v35, v35
	v_pk_fma_f32 v[18:19], v[84:85], v[84:85], 1.0 op_sel_hi:[1,1,0] neg_lo:[1,0,0] neg_hi:[1,0,0]
	v_sqrt_f32_e32 v82, v82
	v_sqrt_f32_e32 v83, v83
	v_sqrt_f32_e32 v18, v18
	v_sqrt_f32_e32 v19, v19
	v_mov_b32_e32 v98, v113
	v_pk_mul_f32 v[50:51], v[98:99], v[50:51] op_sel_hi:[0,1]
	v_pk_mul_f32 v[34:35], v[20:21], v[34:35]
	v_pk_mul_f32 v[82:83], v[102:103], v[82:83]
	v_exp_f32_e32 v103, v50
	v_exp_f32_e32 v104, v51
	v_pk_mul_f32 v[50:51], v[34:35], v[18:19]
	v_pk_add_f32 v[34:35], v[36:37], v[108:109] op_sel_hi:[1,0]
	v_pk_add_f32 v[38:39], v[38:39], v[108:109] op_sel_hi:[1,0]
	v_exp_f32_e32 v34, v34
	v_exp_f32_e32 v35, v35
	v_exp_f32_e32 v38, v38
	v_exp_f32_e32 v39, v39
	v_pk_add_f32 v[18:19], v[52:53], v[110:111] op_sel_hi:[1,0]
	v_pk_add_f32 v[34:35], v[34:35], 1.0 op_sel_hi:[1,0]
	v_exp_f32_e32 v18, v18
	v_rcp_f32_e32 v34, v34
	v_rcp_f32_e32 v35, v35
	v_pk_add_f32 v[38:39], v[38:39], 1.0 op_sel_hi:[1,0]
	v_exp_f32_e32 v19, v19
	v_rcp_f32_e32 v38, v38
	v_pk_mul_f32 v[68:69], v[20:21], v[34:35]
	v_pk_add_f32 v[20:21], v[86:87], v[116:117] op_sel_hi:[1,0]
	v_pk_add_f32 v[34:35], v[70:71], v[114:115] op_sel_hi:[1,0]
	v_exp_f32_e32 v20, v20
	v_exp_f32_e32 v21, v21
	v_exp_f32_e32 v34, v34
	v_exp_f32_e32 v35, v35
	v_rcp_f32_e32 v39, v39
	v_pk_add_f32 v[20:21], v[20:21], 1.0 op_sel_hi:[1,0]
	v_pk_add_f32 v[18:19], v[18:19], 1.0 op_sel_hi:[1,0]
	v_rcp_f32_e32 v20, v20
	v_rcp_f32_e32 v21, v21
	v_pk_add_f32 v[34:35], v[34:35], 1.0 op_sel_hi:[1,0]
	v_pk_mul_f32 v[70:71], v[22:23], v[38:39]
	v_rcp_f32_e32 v36, v34
	v_pk_mul_f32 v[20:21], v[112:113], v[20:21] op_sel_hi:[0,1]
	v_rcp_f32_e32 v37, v35
	v_exp_f32_e32 v34, v20
	v_exp_f32_e32 v35, v21
	v_rcp_f32_e32 v18, v18
	v_pk_mul_f32 v[36:37], v[22:23], v[36:37]
	v_pk_add_f32 v[22:23], v[72:73], v[114:115] op_sel_hi:[1,0]
	v_pk_fma_f32 v[20:21], v[34:35], v[34:35], 1.0 op_sel_hi:[1,1,0] neg_lo:[1,0,0] neg_hi:[1,0,0]
	v_exp_f32_e32 v22, v22
	v_sqrt_f32_e32 v20, v20
	v_sqrt_f32_e32 v21, v21
	v_exp_f32_e32 v23, v23
	v_rcp_f32_e32 v19, v19
	v_fma_f32 v82, 0, v66, v82
	v_pk_mul_f32 v[36:37], v[36:37], v[20:21]
	v_pk_add_f32 v[20:21], v[54:55], v[110:111] op_sel_hi:[1,0]
	v_pk_add_f32 v[22:23], v[22:23], 1.0 op_sel_hi:[1,0]
	v_exp_f32_e32 v20, v20
	v_exp_f32_e32 v21, v21
	v_rcp_f32_e32 v22, v22
	v_rcp_f32_e32 v23, v23
	v_pk_mul_f32 v[18:19], v[98:99], v[18:19] op_sel_hi:[0,1]
	v_pk_add_f32 v[20:21], v[20:21], 1.0 op_sel_hi:[1,0]
	v_exp_f32_e32 v53, v18
	v_rcp_f32_e32 v20, v20
	v_rcp_f32_e32 v21, v21
	v_pk_mul_f32 v[118:119], v[24:25], v[22:23]
	v_fmac_f32_e32 v83, v67, v82
	v_fma_f32 v50, v84, v83, v50
	v_pk_mul_f32 v[20:21], v[98:99], v[20:21] op_sel_hi:[0,1]
	v_exp_f32_e32 v102, v20
	v_exp_f32_e32 v54, v21
	v_pk_add_f32 v[20:21], v[88:89], v[116:117] op_sel_hi:[1,0]
	v_fmac_f32_e32 v51, v85, v50
	v_exp_f32_e32 v20, v20
	v_exp_f32_e32 v21, v21
	v_fma_f32 v36, 0, v34, v36
	v_fmac_f32_e32 v37, v35, v36
	v_mul_f32_e32 v67, v66, v67
	v_pk_add_f32 v[20:21], v[20:21], 1.0 op_sel_hi:[1,0]
	v_mov_b32_e32 v105, v103
	v_rcp_f32_e32 v20, v20
	v_rcp_f32_e32 v21, v21
	v_exp_f32_e32 v19, v19
	v_mov_b32_e32 v87, v102
	v_pk_mul_f32 v[170:171], v[4:5], v[4:5]
	v_pk_mul_f32 v[20:21], v[112:113], v[20:21] op_sel_hi:[0,1]
	v_exp_f32_e32 v109, v21
	v_exp_f32_e32 v38, v20
	v_pk_add_f32 v[20:21], v[56:57], v[110:111] op_sel_hi:[1,0]
	v_pk_mul_f32 v[170:171], v[4:5], v[170:171]
	v_pk_add_f32 v[22:23], v[40:41], v[108:109] op_sel_hi:[1,0]
	v_exp_f32_e32 v20, v20
	v_exp_f32_e32 v22, v22
	v_exp_f32_e32 v23, v23
	v_exp_f32_e32 v21, v21
	v_pk_mul_f32 v[172:173], v[6:7], v[6:7]
	v_pk_add_f32 v[22:23], v[22:23], 1.0 op_sel_hi:[1,0]
	s_nop 0
	v_rcp_f32_e32 v22, v22
	v_rcp_f32_e32 v23, v23
	v_pk_add_f32 v[20:21], v[20:21], 1.0 op_sel_hi:[1,0]
	v_pk_mul_f32 v[172:173], v[6:7], v[172:173]
	v_rcp_f32_e32 v20, v20
	v_pk_mul_f32 v[72:73], v[24:25], v[22:23]
	v_pk_add_f32 v[22:23], v[74:75], v[114:115] op_sel_hi:[1,0]
	v_pk_add_f32 v[24:25], v[42:43], v[108:109] op_sel_hi:[1,0]
	v_exp_f32_e32 v22, v22
	v_exp_f32_e32 v23, v23
	v_exp_f32_e32 v24, v24
	v_exp_f32_e32 v25, v25
	v_rcp_f32_e32 v21, v21
	v_pk_add_f32 v[22:23], v[22:23], 1.0 op_sel_hi:[1,0]
	v_pk_add_f32 v[24:25], v[24:25], 1.0 op_sel_hi:[1,0]
	v_rcp_f32_e32 v22, v22
	v_rcp_f32_e32 v23, v23
	v_rcp_f32_e32 v24, v24
	v_rcp_f32_e32 v25, v25
	v_pk_mul_f32 v[20:21], v[98:99], v[20:21] op_sel_hi:[0,1]
	v_pk_mul_f32 v[56:57], v[26:27], v[22:23]
	v_pk_add_f32 v[22:23], v[58:59], v[110:111] op_sel_hi:[1,0]
	v_pk_mul_f32 v[88:89], v[26:27], v[24:25]
	v_exp_f32_e32 v22, v22
	v_exp_f32_e32 v23, v23
	v_pk_add_f32 v[24:25], v[76:77], v[114:115] op_sel_hi:[1,0]
	v_exp_f32_e32 v52, v20
	v_exp_f32_e32 v24, v24
	v_pk_add_f32 v[22:23], v[22:23], 1.0 op_sel_hi:[1,0]
	v_exp_f32_e32 v25, v25
	v_rcp_f32_e32 v22, v22
	v_rcp_f32_e32 v23, v23
	v_exp_f32_e32 v18, v21
	v_pk_add_f32 v[24:25], v[24:25], 1.0 op_sel_hi:[1,0]
	v_pk_add_f32 v[20:21], v[90:91], v[116:117] op_sel_hi:[1,0]
	v_pk_mul_f32 v[22:23], v[98:99], v[22:23] op_sel_hi:[0,1]
	v_exp_f32_e32 v74, v22
	v_exp_f32_e32 v86, v23
	v_pk_add_f32 v[22:23], v[92:93], v[116:117] op_sel_hi:[1,0]
	v_rcp_f32_e32 v24, v24
	v_exp_f32_e32 v22, v22
	v_exp_f32_e32 v23, v23
	v_rcp_f32_e32 v25, v25
	v_exp_f32_e32 v20, v20
	v_exp_f32_e32 v21, v21
	v_pk_add_f32 v[22:23], v[22:23], 1.0 op_sel_hi:[1,0]
	v_pk_mul_f32 v[76:77], v[28:29], v[24:25]
	v_rcp_f32_e32 v22, v22
	v_rcp_f32_e32 v23, v23
	v_pk_add_f32 v[24:25], v[44:45], v[108:109] op_sel_hi:[1,0]
	v_pk_add_f32 v[20:21], v[20:21], 1.0 op_sel_hi:[1,0]
	v_exp_f32_e32 v24, v24
	v_pk_mul_f32 v[22:23], v[112:113], v[22:23] op_sel_hi:[0,1]
	v_exp_f32_e32 v42, v22
	v_exp_f32_e32 v39, v23
	v_pk_add_f32 v[22:23], v[60:61], v[110:111] op_sel_hi:[1,0]
	v_exp_f32_e32 v25, v25
	v_exp_f32_e32 v22, v22
	v_exp_f32_e32 v23, v23
	v_rcp_f32_e32 v20, v20
	v_pk_add_f32 v[24:25], v[24:25], 1.0 op_sel_hi:[1,0]
	v_rcp_f32_e32 v21, v21
	v_pk_add_f32 v[22:23], v[22:23], 1.0 op_sel_hi:[1,0]
	v_rcp_f32_e32 v24, v24
	v_rcp_f32_e32 v22, v22
	v_rcp_f32_e32 v23, v23
	v_rcp_f32_e32 v25, v25
	v_pk_mul_f32 v[20:21], v[112:113], v[20:21] op_sel_hi:[0,1]
	v_exp_f32_e32 v40, v21
	v_pk_mul_f32 v[22:23], v[98:99], v[22:23] op_sel_hi:[0,1]
	v_exp_f32_e32 v22, v22
	v_exp_f32_e32 v23, v23
	v_pk_mul_f32 v[24:25], v[28:29], v[24:25]
	v_pk_add_f32 v[28:29], v[78:79], v[114:115] op_sel_hi:[1,0]
	v_mul_f32_e32 v58, v34, v35
	v_pk_fma_f32 v[26:27], v[22:23], v[22:23], 1.0 op_sel_hi:[1,1,0] neg_lo:[1,0,0] neg_hi:[1,0,0]
	v_exp_f32_e32 v28, v28
	v_sqrt_f32_e32 v26, v26
	v_sqrt_f32_e32 v27, v27
	v_exp_f32_e32 v29, v29
	v_exp_f32_e32 v20, v20
	v_pk_mul_f32 v[24:25], v[24:25], v[26:27]
	v_pk_add_f32 v[26:27], v[94:95], v[116:117] op_sel_hi:[1,0]
	v_pk_add_f32 v[28:29], v[28:29], 1.0 op_sel_hi:[1,0]
	v_exp_f32_e32 v26, v26
	v_exp_f32_e32 v27, v27
	v_rcp_f32_e32 v28, v28
	v_rcp_f32_e32 v29, v29
	v_fma_f32 v25, 0, v23, v25
	v_pk_add_f32 v[26:27], v[26:27], 1.0 op_sel_hi:[1,0]
	v_fmac_f32_e32 v24, v22, v25
	v_rcp_f32_e32 v26, v26
	v_rcp_f32_e32 v27, v27
	v_pk_mul_f32 v[44:45], v[30:31], v[28:29]
	v_pk_add_f32 v[28:29], v[46:47], v[108:109] op_sel_hi:[1,0]
	v_mov_b32_e32 v46, v39
	v_pk_mul_f32 v[26:27], v[112:113], v[26:27] op_sel_hi:[0,1]
	v_exp_f32_e32 v21, v26
	v_exp_f32_e32 v41, v27
	v_pk_add_f32 v[26:27], v[62:63], v[110:111] op_sel_hi:[1,0]
	v_exp_f32_e32 v28, v28
	v_exp_f32_e32 v26, v26
	v_exp_f32_e32 v27, v27
	v_exp_f32_e32 v29, v29
	v_pk_add_f32 v[26:27], v[26:27], 1.0 op_sel_hi:[1,0]
	s_nop 0
	v_rcp_f32_e32 v26, v26
	v_rcp_f32_e32 v27, v27
	v_pk_add_f32 v[28:29], v[28:29], 1.0 op_sel_hi:[1,0]
	v_pk_mul_f32 v[26:27], v[98:99], v[26:27] op_sel_hi:[0,1]
	v_exp_f32_e32 v120, v26
	v_exp_f32_e32 v121, v27
	v_rcp_f32_e32 v28, v28
	v_rcp_f32_e32 v29, v29
	v_pk_fma_f32 v[26:27], v[120:121], v[120:121], 1.0 op_sel_hi:[1,1,0] neg_lo:[1,0,0] neg_hi:[1,0,0]
	s_nop 0
	v_sqrt_f32_e32 v26, v26
	v_sqrt_f32_e32 v27, v27
	v_pk_mul_f32 v[28:29], v[30:31], v[28:29]
	v_pk_add_f32 v[30:31], v[80:81], v[114:115] op_sel_hi:[1,0]
	v_pk_mul_f32 v[28:29], v[28:29], v[26:27]
	v_exp_f32_e32 v30, v30
	v_exp_f32_e32 v31, v31
	v_pk_add_f32 v[26:27], v[96:97], v[116:117] op_sel_hi:[1,0]
	v_mul_f32_e32 v96, v84, v67
	v_exp_f32_e32 v26, v26
	v_exp_f32_e32 v27, v27
	v_pk_add_f32 v[30:31], v[30:31], 1.0 op_sel_hi:[1,0]
	v_mul_f32_e32 v114, v85, v96
	v_rcp_f32_e32 v30, v30
	v_rcp_f32_e32 v31, v31
	v_pk_add_f32 v[26:27], v[26:27], 1.0 op_sel_hi:[1,0]
	v_mov_b32_e32 v97, v114
	v_rcp_f32_e32 v26, v26
	v_rcp_f32_e32 v27, v27
	v_pk_mul_f32 v[60:61], v[32:33], v[30:31]
	v_pk_add_f32 v[30:31], v[48:49], v[108:109] op_sel_hi:[1,0]
	v_mov_b32_e32 v108, v38
	v_exp_f32_e32 v30, v30
	v_exp_f32_e32 v31, v31
	v_pk_mul_f32 v[26:27], v[112:113], v[26:27] op_sel_hi:[0,1]
	v_exp_f32_e32 v43, v26
	v_exp_f32_e32 v47, v27
	v_pk_add_f32 v[26:27], v[64:65], v[110:111] op_sel_hi:[1,0]
	v_pk_add_f32 v[30:31], v[30:31], 1.0 op_sel_hi:[1,0]
	v_exp_f32_e32 v26, v26
	v_exp_f32_e32 v27, v27
	v_rcp_f32_e32 v30, v30
	v_rcp_f32_e32 v31, v31
	ds_bpermute_b32 v64, v176, v114
	v_pk_add_f32 v[26:27], v[26:27], 1.0 op_sel_hi:[1,0]
	v_pk_mul_f32 v[30:31], v[32:33], v[30:31]
	v_rcp_f32_e32 v26, v26
	v_rcp_f32_e32 v27, v27
	ds_bpermute_b32 v32, v176, v51
	s_waitcnt lgkmcnt(1)
	v_cndmask_b32_e64 v110, v64, 1.0, s[40:41]
	v_pk_mul_f32 v[26:27], v[98:99], v[26:27] op_sel_hi:[0,1]
	v_exp_f32_e32 v26, v26
	v_exp_f32_e32 v27, v27
	s_waitcnt lgkmcnt(0)
	v_cndmask_b32_e64 v35, v32, v51, s[40:41]
	v_cndmask_b32_e64 v55, v51, v32, s[40:41]
	v_pk_fma_f32 v[32:33], v[108:109], v[108:109], 1.0 op_sel_hi:[1,1,0] neg_lo:[1,0,0] neg_hi:[1,0,0]
	v_pk_fma_f32 v[48:49], v[26:27], v[26:27], 1.0 op_sel_hi:[1,1,0] neg_lo:[1,0,0] neg_hi:[1,0,0]
	v_sqrt_f32_e32 v32, v32
	v_sqrt_f32_e32 v33, v33
	v_sqrt_f32_e32 v48, v48
	v_sqrt_f32_e32 v49, v49
	v_pk_mul_f32 v[92:93], v[118:119], v[32:33]
	v_mov_b32_e32 v32, v20
	v_mov_b32_e32 v33, v40
	v_pk_fma_f32 v[32:33], v[32:33], v[32:33], 1.0 op_sel_hi:[1,1,0] neg_lo:[1,0,0] neg_hi:[1,0,0]
	v_pk_mul_f32 v[30:31], v[30:31], v[48:49]
	v_sqrt_f32_e32 v32, v32
	v_sqrt_f32_e32 v33, v33
	v_mov_b32_e32 v48, v21
	v_mov_b32_e32 v49, v41
	v_pk_fma_f32 v[48:49], v[48:49], v[48:49], 1.0 op_sel_hi:[1,1,0] neg_lo:[1,0,0] neg_hi:[1,0,0]
	v_pk_mul_f32 v[90:91], v[56:57], v[32:33]
	v_sqrt_f32_e32 v48, v48
	v_sqrt_f32_e32 v49, v49
	v_mov_b32_e32 v32, v42
	v_mov_b32_e32 v33, v39
	v_pk_fma_f32 v[32:33], v[32:33], v[32:33], 1.0 op_sel_hi:[1,1,0] neg_lo:[1,0,0] neg_hi:[1,0,0]
	v_pk_mul_f32 v[56:57], v[44:45], v[48:49]
	v_sqrt_f32_e32 v32, v32
	v_sqrt_f32_e32 v33, v33
	v_mov_b32_e32 v44, v43
	v_mov_b32_e32 v45, v47
	v_pk_fma_f32 v[48:49], v[44:45], v[44:45], 1.0 op_sel_hi:[1,1,0] neg_lo:[1,0,0] neg_hi:[1,0,0]
	v_fma_f32 v90, 0, v20, v90
	v_sqrt_f32_e32 v48, v48
	v_sqrt_f32_e32 v49, v49
	v_pk_mul_f32 v[32:33], v[76:77], v[32:33]
	v_fmac_f32_e32 v91, v40, v90
	v_fma_f32 v59, v42, v91, v32
	v_fma_f32 v92, v38, v37, v92
	v_pk_mul_f32 v[94:95], v[38:39], v[58:59]
	v_mov_b32_e32 v32, v109
	v_pk_mul_f32 v[60:61], v[60:61], v[48:49]
	v_fmac_f32_e32 v93, v109, v92
	v_pk_mul_f32 v[108:109], v[32:33], v[94:95]
	v_fma_f32 v56, 0, v21, v56
	v_pk_mul_f32 v[48:49], v[20:21], v[40:41]
	ds_bpermute_b32 v65, v176, v108
	ds_bpermute_b32 v75, v176, v93
	v_fmac_f32_e32 v57, v41, v56
	v_pk_mul_f32 v[62:63], v[42:43], v[48:49]
	v_fma_f32 v41, v43, v57, v60
	v_mov_b32_e32 v40, v49
	v_pk_mul_f32 v[80:81], v[46:47], v[62:63]
	v_pk_fma_f32 v[76:77], v[38:39], v[58:59], v[32:33]
	v_pk_mul_f32 v[38:39], v[44:45], v[40:41]
	ds_bpermute_b32 v63, v176, v80
	v_mov_b32_e32 v60, v47
	ds_bpermute_b32 v76, v176, v77
	v_pk_mul_f32 v[46:47], v[60:61], v[38:39]
	v_cndmask_b32_e64 v39, v64, v114, s[40:41]
	v_pk_fma_f32 v[32:33], v[44:45], v[40:41], v[60:61]
	v_cndmask_b32_e64 v40, v114, v64, s[40:41]
	v_fmac_f32_e32 v35, 0, v39
	v_fmac_f32_e32 v55, v40, v35
	v_cndmask_b32_e64 v118, v35, 0, s[40:41]
	s_waitcnt lgkmcnt(2)
	v_cndmask_b32_e64 v35, v75, v93, s[40:41]
	v_cndmask_b32_e64 v42, v65, v108, s[40:41]
	v_cndmask_b32_e64 v39, v93, v75, s[40:41]
	v_fmac_f32_e32 v35, v42, v55
	v_cndmask_b32_e64 v60, v108, v65, s[40:41]
	v_fmac_f32_e32 v39, v60, v35
	s_waitcnt lgkmcnt(1)
	v_cndmask_b32_e64 v78, v63, v80, s[40:41]
	ds_bpermute_b32 v32, v176, v46
	s_waitcnt lgkmcnt(1)
	v_cndmask_b32_e64 v65, v76, v77, s[40:41]
	v_mul_f32_e32 v115, v78, v39
	ds_bpermute_b32 v45, v176, v33
	v_pk_mul_f32 v[84:85], v[114:115], v[64:65]
	v_pk_add_f32 v[64:65], v[114:115], v[64:65]
	v_cndmask_b32_e64 v43, v80, v63, s[40:41]
	v_mov_b32_e32 v85, v65
	v_cndmask_b32_e64 v61, v77, v76, s[40:41]
	v_pk_mul_f32 v[116:117], v[84:85], v[42:43]
	s_waitcnt lgkmcnt(1)
	v_cndmask_b32_e64 v79, v32, v81, s[40:41]
	v_cndmask_b32_e64 v76, v116, v84, s[40:41]
	v_pk_mul_f32 v[116:117], v[60:61], v[116:117]
	v_pk_fma_f32 v[60:61], v[84:85], v[42:43], v[60:61]
	s_waitcnt lgkmcnt(0)
	v_cndmask_b32_e64 v113, v45, v33, s[40:41]
	v_mov_b32_e32 v117, v61
	v_mov_b32_e32 v112, v43
	v_cndmask_b32_e64 v84, v65, v39, s[40:41]
	v_pk_mul_f32 v[64:65], v[78:79], v[116:117]
	v_cndmask_b32_e64 v40, v46, v32, s[40:41]
	v_cndmask_b32_e64 v42, v32, v46, s[40:41]
	v_cndmask_b32_e64 v32, v64, v116, s[40:41]
	v_pk_mul_f32 v[64:65], v[112:113], v[64:65]
	v_pk_fma_f32 v[78:79], v[78:79], v[116:117], v[112:113]
	v_mov_b32_e32 v43, v40
	v_mov_b32_e32 v65, v79
	v_pk_mul_f32 v[42:43], v[42:43], v[64:65]
	v_mov_b32_e32 v75, v86
	v_cndmask_b32_e64 v44, v42, v64, s[40:41]
	v_pk_fma_f32 v[64:65], v[104:105], v[104:105], 1.0 op_sel_hi:[1,1,0] neg_lo:[1,0,0] neg_hi:[1,0,0]
	v_fma_f32 v31, 0, v27, v31
	v_sqrt_f32_e32 v112, v65
	v_sqrt_f32_e32 v113, v64
	v_fmac_f32_e32 v30, v26, v31
	v_mul_f32_e32 v26, v27, v26
	v_cndmask_b32_e64 v98, v35, v55, s[40:41]
	v_pk_mul_f32 v[64:65], v[106:107], v[112:113]
	v_mov_b32_e32 v106, v53
	v_mov_b32_e32 v107, v19
	v_pk_fma_f32 v[106:107], v[106:107], v[106:107], 1.0 op_sel_hi:[1,1,0] neg_lo:[1,0,0] neg_hi:[1,0,0]
	v_pk_mul_f32 v[112:113], v[18:19], v[52:53]
	v_sqrt_f32_e32 v106, v106
	v_sqrt_f32_e32 v107, v107
	v_fma_f32 v29, v121, v30, v29
	v_mul_f32_e32 v39, v121, v26
	v_mov_b32_e32 v55, v104
	v_pk_mul_f32 v[128:129], v[68:69], v[106:107]
	v_mov_b32_e32 v68, v102
	v_mov_b32_e32 v69, v54
	v_pk_fma_f32 v[68:69], v[68:69], v[68:69], 1.0 op_sel_hi:[1,1,0] neg_lo:[1,0,0] neg_hi:[1,0,0]
	v_fma_f32 v129, 0, v19, v129
	v_sqrt_f32_e32 v68, v68
	v_sqrt_f32_e32 v69, v69
	v_fmac_f32_e32 v128, v53, v129
	v_cndmask_b32_e64 v60, v79, v61, s[40:41]
	v_mul_f32_e32 v78, v23, v22
	v_pk_mul_f32 v[68:69], v[70:71], v[68:69]
	v_mov_b32_e32 v70, v52
	v_mov_b32_e32 v71, v18
	v_pk_fma_f32 v[70:71], v[70:71], v[70:71], 1.0 op_sel_hi:[1,1,0] neg_lo:[1,0,0] neg_hi:[1,0,0]
	v_fmac_f32_e32 v28, v120, v29
	v_sqrt_f32_e32 v70, v70
	v_sqrt_f32_e32 v71, v71
	v_pk_mul_f32 v[124:125], v[54:55], v[112:113]
	ds_bpermute_b32 v22, v176, v28
	v_pk_fma_f32 v[114:115], v[170:171], s[54:55], v[4:5] op_sel_hi:[1,0,1]
	v_pk_mul_f32 v[116:117], v[72:73], v[70:71]
	v_pk_fma_f32 v[70:71], v[74:75], v[74:75], 1.0 op_sel_hi:[1,1,0] neg_lo:[1,0,0] neg_hi:[1,0,0]
	v_fma_f32 v117, 0, v18, v117
	v_sqrt_f32_e32 v70, v70
	v_sqrt_f32_e32 v71, v71
	v_fmac_f32_e32 v116, v52, v117
	v_fma_f32 v79, v54, v116, v69
	v_mov_b32_e32 v75, v68
	v_pk_mul_f32 v[106:107], v[88:89], v[70:71]
	v_fma_f32 v71, v104, v128, v65
	v_mov_b32_e32 v70, v113
	v_pk_mul_f32 v[130:131], v[104:105], v[70:71]
	v_pk_mov_b32 v[64:65], v[104:105], v[64:65] op_sel:[1,0]
	v_mul_f32_e32 v68, v120, v39
	v_pk_mul_f32 v[132:133], v[64:65], v[130:131]
	v_pk_fma_f32 v[64:65], v[104:105], v[70:71], v[64:65]
	v_pk_mul_f32 v[104:105], v[102:103], v[124:125]
	v_pk_mul_f32 v[102:103], v[86:87], v[78:79]
	v_fma_f32 v107, v86, v24, v107
	ds_bpermute_b32 v52, v176, v68
	v_pk_mul_f32 v[88:89], v[74:75], v[102:103]
	v_fmac_f32_e32 v106, v74, v107
	ds_bpermute_b32 v69, v176, v88
	ds_bpermute_b32 v70, v176, v106
	ds_bpermute_b32 v63, v176, v104
	v_pk_fma_f32 v[54:55], v[86:87], v[78:79], v[74:75]
	s_waitcnt lgkmcnt(4)
	v_cndmask_b32_e64 v35, v22, v28, s[40:41]
	v_cndmask_b32_e64 v22, v28, v22, s[40:41]
	ds_bpermute_b32 v53, v176, v55
	s_waitcnt lgkmcnt(4)
	v_cndmask_b32_e64 v64, v68, v52, s[40:41]
	v_cndmask_b32_e64 v54, v52, v68, s[40:41]
	v_fmac_f32_e32 v22, 0, v64
	v_fmac_f32_e32 v35, v54, v22
	v_cndmask_b32_e64 v64, 0, v22, s[40:41]
	s_waitcnt lgkmcnt(2)
	v_cndmask_b32_e64 v22, v70, v106, s[40:41]
	v_cndmask_b32_e64 v70, v106, v70, s[40:41]
	v_cndmask_b32_e64 v74, v88, v69, s[40:41]
	ds_bpermute_b32 v61, v176, v132
	ds_bpermute_b32 v47, v176, v65
	v_fmac_f32_e32 v70, v74, v35
	v_cndmask_b32_e64 v120, v69, v88, s[40:41]
	v_pk_mul_f32 v[176:177], v[2:3], v[2:3]
	v_fmac_f32_e32 v22, v120, v70
	s_waitcnt lgkmcnt(3)
	v_cndmask_b32_e64 v162, v104, v63, s[40:41]
	v_pk_mul_f32 v[176:177], v[2:3], v[176:177]
	s_waitcnt lgkmcnt(2)
	v_cndmask_b32_e64 v121, v53, v55, s[40:41]
	v_cndmask_b32_e64 v53, v55, v53, s[40:41]
	v_mul_f32_e32 v69, v162, v22
	v_pk_fma_f32 v[176:177], v[176:177], s[54:55], v[2:3] op_sel_hi:[1,0,1]
	v_cndmask_b32_e64 v54, 1.0, v52, s[40:41]
	v_pk_mul_f32 v[122:123], v[68:69], v[52:53]
	v_pk_add_f32 v[52:53], v[68:69], v[52:53]
	v_pk_mul_f32 v[176:177], v[176:177], s[28:29] op_sel_hi:[1,0]
	v_cndmask_b32_e64 v75, v63, v104, s[40:41]
	v_mov_b32_e32 v123, v53
	v_exp_f32_e32 v176, v176
	v_exp_f32_e32 v177, v177
	v_pk_mul_f32 v[126:127], v[122:123], v[74:75]
	v_mov_b32_e32 v164, v75
	v_pk_mul_f32 v[166:167], v[120:121], v[126:127]
	v_pk_fma_f32 v[74:75], v[122:123], v[74:75], v[120:121]
	s_waitcnt lgkmcnt(1)
	v_cndmask_b32_e64 v163, v105, v61, s[40:41]
	v_mov_b32_e32 v167, v75
	s_waitcnt lgkmcnt(0)
	v_cndmask_b32_e64 v165, v65, v47, s[40:41]
	v_pk_mul_f32 v[120:121], v[162:163], v[166:167]
	v_pk_add_f32 v[176:177], v[176:177], 1.0 op_sel_hi:[1,0]
	v_pk_mul_f32 v[114:115], v[114:115], s[28:29] op_sel_hi:[1,0]
	v_cndmask_b32_e64 v72, v122, v126, s[40:41]
	v_cndmask_b32_e64 v126, v22, v53, s[40:41]
	v_cndmask_b32_e64 v22, v61, v132, s[40:41]
	v_cndmask_b32_e64 v122, v166, v120, s[40:41]
	v_pk_mul_f32 v[120:121], v[164:165], v[120:121]
	v_pk_fma_f32 v[162:163], v[162:163], v[166:167], v[164:165]
	v_rcp_f32_e32 v176, v176
	v_rcp_f32_e32 v177, v177
	v_exp_f32_e32 v114, v114
	v_exp_f32_e32 v115, v115
	v_cndmask_b32_e64 v52, v132, v61, s[40:41]
	v_mov_b32_e32 v53, v22
	v_mov_b32_e32 v121, v163
	v_cndmask_b32_e64 v86, v35, v70, s[40:41]
	v_pk_mul_f32 v[52:53], v[52:53], v[120:121]
	v_cndmask_b32_e64 v162, v75, v163, s[40:41]
	v_mov_b32_e32 v133, v130
	v_mov_b32_e32 v70, v65
	v_cndmask_b32_e64 v164, v120, v52, s[40:41]
	v_pk_fma_f32 v[166:167], v[66:67], v[118:119], v[82:83] op_sel_hi:[1,0,1]
	v_pk_fma_f32 v[168:169], v[132:133], v[162:163], v[70:71] op_sel_hi:[1,0,1]
	v_pk_mul_f32 v[2:3], v[2:3], v[176:177]
	v_pk_add_f32 v[166:167], v[166:167], v[168:169]
	v_pk_mul_f32 v[66:67], v[110:111], v[66:67] op_sel_hi:[0,1]
	v_pk_mul_f32 v[132:133], v[132:133], v[164:165] op_sel_hi:[1,0]
	v_pk_add_f32 v[114:115], v[114:115], 1.0 op_sel_hi:[1,0]
	v_pk_mul_f32 v[166:167], v[2:3], v[166:167]
	v_pk_mul_f32 v[66:67], v[2:3], v[66:67]
	v_pk_mul_f32 v[2:3], v[2:3], v[132:133]
	v_rcp_f32_e32 v114, v114
	v_rcp_f32_e32 v115, v115
	v_cvt_pk_bf16_f32 v35, v166, v167
	v_cvt_pk_bf16_f32 v2, v2, v3
	v_cvt_pk_bf16_f32 v61, v66, v67
	ds_write_b16 v161, v35 offset:49152
	ds_write_b16_d16_hi v161, v35 offset:49232
	ds_write_b16 v161, v61 offset:51712
	ds_write_b16_d16_hi v161, v61 offset:51792
	ds_write_b16 v161, v2 offset:54272
	ds_write_b16_d16_hi v161, v2 offset:54352
	v_mov_b32_e32 v2, v113
	v_mov_b32_e32 v3, v19
	v_pk_fma_f32 v[50:51], v[96:97], v[118:119], v[50:51] op_sel_hi:[1,0,1]
	v_pk_fma_f32 v[66:67], v[2:3], v[162:163], v[128:129] op_sel_hi:[1,0,1]
	v_pk_mul_f32 v[4:5], v[4:5], v[114:115]
	v_pk_add_f32 v[50:51], v[50:51], v[66:67]
	v_pk_mul_f32 v[2:3], v[2:3], v[164:165] op_sel_hi:[1,0]
	v_pk_mul_f32 v[50:51], v[4:5], v[50:51]
	v_pk_mul_f32 v[66:67], v[110:111], v[96:97] op_sel_hi:[0,1]
	v_pk_mul_f32 v[2:3], v[4:5], v[2:3]
	v_pk_mul_f32 v[66:67], v[4:5], v[66:67]
	v_cvt_pk_bf16_f32 v4, v50, v51
	v_cvt_pk_bf16_f32 v2, v2, v3
	v_mov_b32_e32 v35, v58
	v_cvt_pk_bf16_f32 v5, v66, v67
	ds_write_b16 v161, v4 offset:49312
	ds_write_b16_d16_hi v161, v4 offset:49392
	ds_write_b16 v161, v5 offset:51872
	ds_write_b16_d16_hi v161, v5 offset:51952
	ds_write_b16 v161, v2 offset:54432
	ds_write_b16_d16_hi v161, v2 offset:54512
	v_pk_fma_f32 v[2:3], v[34:35], v[98:99], v[36:37] op_sel_hi:[1,0,1]
	v_pk_fma_f32 v[36:37], v[172:173], s[54:55], v[6:7] op_sel_hi:[1,0,1]
	v_mov_b32_e32 v105, v124
	v_pk_mul_f32 v[36:37], v[36:37], s[28:29] op_sel_hi:[1,0]
	v_mov_b32_e32 v4, v55
	v_exp_f32_e32 v36, v36
	v_exp_f32_e32 v37, v37
	v_mov_b32_e32 v5, v79
	v_pk_fma_f32 v[4:5], v[104:105], v[126:127], v[4:5] op_sel_hi:[1,0,1]
	v_pk_mul_f32 v[130:131], v[8:9], v[8:9]
	v_pk_add_f32 v[36:37], v[36:37], 1.0 op_sel_hi:[1,0]
	v_pk_add_f32 v[2:3], v[2:3], v[4:5]
	v_rcp_f32_e32 v36, v36
	v_rcp_f32_e32 v37, v37
	v_pk_mul_f32 v[4:5], v[34:35], v[76:77] op_sel_hi:[1,0]
	v_pk_mul_f32 v[34:35], v[104:105], v[122:123] op_sel_hi:[1,0]
	v_pk_mul_f32 v[130:131], v[8:9], v[130:131]
	v_pk_mul_f32 v[6:7], v[6:7], v[36:37]
	v_mov_b32_e32 v95, v108
	v_pk_mul_f32 v[2:3], v[6:7], v[2:3]
	v_pk_mul_f32 v[4:5], v[6:7], v[4:5]
	v_pk_mul_f32 v[6:7], v[6:7], v[34:35]
	v_cvt_pk_bf16_f32 v2, v2, v3
	v_cvt_pk_bf16_f32 v3, v4, v5
	v_cvt_pk_bf16_f32 v4, v6, v7
	v_pk_fma_f32 v[6:7], v[130:131], s[54:55], v[8:9] op_sel_hi:[1,0,1]
	v_mov_b32_e32 v113, v18
	v_pk_mul_f32 v[6:7], v[6:7], s[28:29] op_sel_hi:[1,0]
	v_pk_mul_f32 v[120:121], v[10:11], v[10:11]
	v_exp_f32_e32 v6, v6
	v_exp_f32_e32 v7, v7
	ds_write_b16 v161, v2 offset:49792
	ds_write_b16_d16_hi v161, v2 offset:49872
	ds_write_b16 v161, v3 offset:52352
	ds_write_b16_d16_hi v161, v3 offset:52432
	ds_write_b16 v161, v4 offset:54912
	ds_write_b16_d16_hi v161, v4 offset:54992
	v_pk_fma_f32 v[2:3], v[94:95], v[98:99], v[92:93] op_sel_hi:[1,0,1]
	v_pk_fma_f32 v[4:5], v[112:113], v[126:127], v[116:117] op_sel_hi:[1,0,1]
	v_pk_add_f32 v[6:7], v[6:7], 1.0 op_sel_hi:[1,0]
	v_pk_mul_f32 v[120:121], v[10:11], v[120:121]
	v_rcp_f32_e32 v6, v6
	v_rcp_f32_e32 v7, v7
	v_pk_add_f32 v[2:3], v[2:3], v[4:5]
	v_pk_mul_f32 v[4:5], v[94:95], v[76:77] op_sel_hi:[1,0]
	v_mov_b32_e32 v89, v102
	v_pk_mul_f32 v[6:7], v[8:9], v[6:7]
	v_pk_mul_f32 v[8:9], v[112:113], v[122:123] op_sel_hi:[1,0]
	v_pk_mul_f32 v[2:3], v[6:7], v[2:3]
	v_pk_mul_f32 v[4:5], v[6:7], v[4:5]
	v_pk_mul_f32 v[6:7], v[6:7], v[8:9]
	v_pk_fma_f32 v[8:9], v[120:121], s[54:55], v[10:11] op_sel_hi:[1,0,1]
	v_cvt_pk_bf16_f32 v2, v2, v3
	v_pk_mul_f32 v[8:9], v[8:9], s[28:29] op_sel_hi:[1,0]
	v_cvt_pk_bf16_f32 v3, v4, v5
	v_exp_f32_e32 v8, v8
	v_exp_f32_e32 v9, v9
	v_cvt_pk_bf16_f32 v4, v6, v7
	ds_write_b16 v161, v2 offset:49952
	ds_write_b16_d16_hi v161, v2 offset:50032
	ds_write_b16 v161, v3 offset:52512
	ds_write_b16_d16_hi v161, v3 offset:52592
	ds_write_b16 v161, v4 offset:55072
	ds_write_b16_d16_hi v161, v4 offset:55152
	v_mov_b32_e32 v2, v20
	v_pk_add_f32 v[8:9], v[8:9], 1.0 op_sel_hi:[1,0]
	v_mov_b32_e32 v3, v48
	v_rcp_f32_e32 v8, v8
	v_rcp_f32_e32 v9, v9
	v_pk_fma_f32 v[4:5], v[2:3], v[84:85], v[90:91] op_sel_hi:[1,0,1]
	v_pk_fma_f32 v[6:7], v[88:89], v[86:87], v[106:107] op_sel_hi:[1,0,1]
	v_pk_mul_f32 v[82:83], v[12:13], v[12:13]
	v_pk_mul_f32 v[8:9], v[10:11], v[8:9]
	v_pk_add_f32 v[4:5], v[6:7], v[4:5]
	v_pk_mul_f32 v[2:3], v[2:3], v[32:33] op_sel_hi:[1,0]
	v_pk_mul_f32 v[6:7], v[88:89], v[72:73] op_sel_hi:[1,0]
	v_pk_mul_f32 v[82:83], v[12:13], v[82:83]
	v_pk_mul_f32 v[2:3], v[8:9], v[2:3]
	v_pk_mul_f32 v[6:7], v[8:9], v[6:7]
	v_cvt_pk_bf16_f32 v2, v2, v3
	v_cvt_pk_bf16_f32 v3, v6, v7
	v_pk_fma_f32 v[6:7], v[82:83], s[54:55], v[12:13] op_sel_hi:[1,0,1]
	v_pk_mul_f32 v[4:5], v[8:9], v[4:5]
	v_pk_mul_f32 v[6:7], v[6:7], s[28:29] op_sel_hi:[1,0]
	v_cvt_pk_bf16_f32 v4, v4, v5
	v_exp_f32_e32 v6, v6
	v_exp_f32_e32 v7, v7
	v_mov_b32_e32 v63, v80
	v_mov_b32_e32 v79, v23
	v_mov_b32_e32 v76, v59
	v_pk_add_f32 v[6:7], v[6:7], 1.0 op_sel_hi:[1,0]
	ds_write_b16 v161, v4 offset:50432
	ds_write_b16_d16_hi v161, v4 offset:50512
	ds_write_b16 v161, v2 offset:52992
	ds_write_b16_d16_hi v161, v2 offset:53072
	ds_write_b16 v161, v3 offset:55552
	ds_write_b16_d16_hi v161, v3 offset:55632
	v_rcp_f32_e32 v6, v6
	v_rcp_f32_e32 v7, v7
	v_pk_fma_f32 v[2:3], v[62:63], v[84:85], v[76:77] op_sel_hi:[1,0,1]
	v_pk_fma_f32 v[4:5], v[78:79], v[86:87], v[24:25] op_sel_hi:[1,0,1]
	v_pk_mul_f32 v[74:75], v[14:15], v[14:15]
	v_pk_mul_f32 v[6:7], v[12:13], v[6:7]
	v_pk_add_f32 v[2:3], v[4:5], v[2:3]
	v_pk_mul_f32 v[4:5], v[62:63], v[32:33] op_sel_hi:[1,0]
	v_pk_mul_f32 v[8:9], v[78:79], v[72:73] op_sel_hi:[1,0]
	v_pk_mul_f32 v[74:75], v[14:15], v[74:75]
	v_pk_mul_f32 v[2:3], v[6:7], v[2:3]
	v_pk_mul_f32 v[4:5], v[6:7], v[4:5]
	v_pk_mul_f32 v[6:7], v[6:7], v[8:9]
	v_cvt_pk_bf16_f32 v2, v2, v3
	v_cvt_pk_bf16_f32 v3, v4, v5
	v_cvt_pk_bf16_f32 v4, v6, v7
	v_pk_fma_f32 v[6:7], v[74:75], s[54:55], v[14:15] op_sel_hi:[1,0,1]
	v_mov_b32_e32 v48, v21
	v_pk_mul_f32 v[6:7], v[6:7], s[28:29] op_sel_hi:[1,0]
	v_mov_b32_e32 v69, v39
	v_exp_f32_e32 v6, v6
	v_exp_f32_e32 v7, v7
	ds_write_b16 v161, v2 offset:50592
	ds_write_b16_d16_hi v161, v2 offset:50672
	ds_write_b16 v161, v3 offset:53152
	ds_write_b16_d16_hi v161, v3 offset:53232
	ds_write_b16 v161, v4 offset:55712
	ds_write_b16_d16_hi v161, v4 offset:55792
	v_pk_fma_f32 v[2:3], v[48:49], v[60:61], v[56:57] op_sel_hi:[1,0,1]
	v_pk_fma_f32 v[4:5], v[68:69], v[64:65], v[28:29] op_sel_hi:[1,0,1]
	v_pk_add_f32 v[6:7], v[6:7], 1.0 op_sel_hi:[1,0]
	v_pk_mul_f32 v[70:71], v[16:17], v[16:17]
	v_rcp_f32_e32 v6, v6
	v_rcp_f32_e32 v7, v7
	v_pk_add_f32 v[2:3], v[4:5], v[2:3]
	v_pk_mul_f32 v[4:5], v[48:49], v[44:45] op_sel_hi:[1,0]
	v_pk_mul_f32 v[8:9], v[68:69], v[54:55] op_sel_hi:[1,0]
	v_pk_mul_f32 v[6:7], v[14:15], v[6:7]
	v_pk_mul_f32 v[70:71], v[16:17], v[70:71]
	v_pk_mul_f32 v[2:3], v[6:7], v[2:3]
	v_pk_mul_f32 v[4:5], v[6:7], v[4:5]
	v_pk_mul_f32 v[6:7], v[6:7], v[8:9]
	v_cvt_pk_bf16_f32 v2, v2, v3
	v_cvt_pk_bf16_f32 v3, v4, v5
	v_cvt_pk_bf16_f32 v4, v6, v7
	v_pk_fma_f32 v[6:7], v[70:71], s[54:55], v[16:17] op_sel_hi:[1,0,1]
	v_mov_b32_e32 v39, v46
	v_pk_mul_f32 v[6:7], v[6:7], s[28:29] op_sel_hi:[1,0]
	v_mov_b32_e32 v32, v41
	v_exp_f32_e32 v6, v6
	v_exp_f32_e32 v7, v7
	ds_write_b16 v161, v2 offset:51072
	ds_write_b16_d16_hi v161, v2 offset:51152
	ds_write_b16 v161, v3 offset:53632
	ds_write_b16_d16_hi v161, v3 offset:53712
	ds_write_b16 v161, v4 offset:56192
	ds_write_b16_d16_hi v161, v4 offset:56272
	v_pk_fma_f32 v[2:3], v[38:39], v[60:61], v[32:33] op_sel_hi:[1,0,1]
	v_pk_fma_f32 v[4:5], v[26:27], v[64:65], v[30:31] op_sel_hi:[1,0,1]
	v_pk_add_f32 v[6:7], v[6:7], 1.0 op_sel_hi:[1,0]
	v_pk_add_f32 v[2:3], v[4:5], v[2:3]
	v_rcp_f32_e32 v6, v6
	v_rcp_f32_e32 v7, v7
	v_pk_mul_f32 v[4:5], v[38:39], v[44:45] op_sel_hi:[1,0]
	v_pk_mul_f32 v[8:9], v[26:27], v[54:55] op_sel_hi:[1,0]
	v_pk_mul_f32 v[6:7], v[16:17], v[6:7]
	s_nop 0
	v_pk_mul_f32 v[2:3], v[6:7], v[2:3]
	v_pk_mul_f32 v[4:5], v[6:7], v[4:5]
	v_pk_mul_f32 v[6:7], v[6:7], v[8:9]
	v_cvt_pk_bf16_f32 v2, v2, v3
	v_cvt_pk_bf16_f32 v3, v4, v5
	v_cvt_pk_bf16_f32 v4, v6, v7
	ds_write_b16 v161, v2 offset:51232
	ds_write_b16_d16_hi v161, v2 offset:51312
	ds_write_b16 v161, v3 offset:53792
	ds_write_b16_d16_hi v161, v3 offset:53872
	ds_write_b16 v161, v4 offset:56352
	ds_write_b16_d16_hi v161, v4 offset:56432
	s_waitcnt lgkmcnt(0)
	ds_read_b128 v[2:5], v160 offset:49152
	ds_read_b128 v[6:9], v160 offset:49168
	ds_read_b128 v[10:13], v160 offset:51712
	ds_read_b128 v[14:17], v160 offset:51728
	ds_read_b128 v[18:21], v160 offset:54272
	ds_read_b128 v[24:27], v160 offset:54288
	s_waitcnt lgkmcnt(0)
	s_waitcnt lgkmcnt(5)
	global_store_dwordx4 v[148:149], v[2:5], off offset:64
	s_waitcnt lgkmcnt(4)
	global_store_dwordx4 v[150:151], v[6:9], off offset:80
	s_waitcnt lgkmcnt(3)
	global_store_dwordx4 v[152:153], v[10:13], off offset:64
	s_waitcnt lgkmcnt(2)
	global_store_dwordx4 v[154:155], v[14:17], off offset:80
	s_waitcnt lgkmcnt(1)
	global_store_dwordx4 v[156:157], v[18:21], off offset:64
	s_waitcnt lgkmcnt(0)
	global_store_dwordx4 v[158:159], v[24:27], off offset:80
	s_and_saveexec_b64 s[0:1], s[38:39]
	s_cbranch_execz .LBB0_475
	v_lshl_add_u64 v[2:3], s[10:11], 0, v[134:135]
	v_add_co_u32_e32 v4, vcc, 0x18000000, v2
	s_nop 1
	v_addc_co_u32_e32 v5, vcc, 0, v3, vcc
	v_add_co_u32_e32 v2, vcc, 0xa00000, v2
	global_store_dwordx2 v[4:5], v[146:147], off
	s_nop 0
	v_addc_co_u32_e32 v3, vcc, 0, v3, vcc
	global_store_dwordx2 v[2:3], v[100:101], off
